# k19 + sigmoid gates stored as accumulator-order tiles inside PROJ gate columns (P4c stores, P7 EpiBranch loads 1 KiB contiguous per wave instruction)
# speedup vs baseline: 1.0039x; 1.0039x over previous
.LBB0_613:
	s_lshl_b32 s100, s48, 5
	s_add_i32 s100, s100, s67
	s_lshl_b32 s100, s100, 3
	s_mov_b32 s101, 0x9000
	v_lshrrev_b32_e32 v224, 6, v0
	v_and_b32_e32 v225, 63, v0
	v_add_u32_e32 v224, s100, v224
	v_mul_lo_u32 v224, v224, s101
	v_lshl_add_u32 v224, v225, 4, v224
	v_mov_b32_e32 v225, 0
	v_lshl_add_u64 v[224:225], s[16:17], 0, v[224:225]
	s_mov_b32 s101, 0
	v_lshl_or_b32 v156, s67, 8, v162
	v_ashrrev_i32_e32 v157, 31, v156
	v_lshl_add_u32 v152, s48, 8, v1
	v_lshl_add_u64 v[150:151], v[156:157], 2, s[18:19]
	v_ashrrev_i32_e32 v153, 31, v152
	global_load_dwordx4 v[166:169], v[150:151], off offset:16
	global_load_dwordx4 v[158:161], v[150:151], off
	v_lshl_add_u64 v[148:149], v[152:153], 2, s[26:27]
	global_load_dword v153, v[148:149], off
	global_load_dword v190, v[148:149], off
	global_load_dword v192, v[148:149], off offset:64
	global_load_dword v194, v[148:149], off offset:128
	global_load_dword v196, v[148:149], off offset:192
	global_load_dword v198, v[148:149], off offset:512
	global_load_dword v200, v[148:149], off offset:576
	global_load_dword v202, v[148:149], off offset:640
	global_load_dword v204, v[148:149], off offset:704
	global_load_dwordx4 v[206:209], v[150:151], off offset:512
	global_load_dwordx4 v[210:213], v[150:151], off offset:528
	v_cvt_f32_i32_e32 v172, v126
	v_cvt_f32_i32_e32 v173, v127
	v_cvt_f32_i32_e32 v174, v128
	v_cvt_f32_i32_e32 v175, v129
	v_cvt_f32_i32_e32 v176, v122
	v_cvt_f32_i32_e32 v177, v123
	v_cvt_f32_i32_e32 v178, v124
	v_cvt_f32_i32_e32 v179, v125
	v_or_b32_e32 v170, 16, v152
	v_lshlrev_b64 v[128:129], 1, v[156:157]
	v_ashrrev_i32_e32 v171, 31, v170
	v_lshl_add_u64 v[124:125], v[170:171], 2, s[26:27]
	s_cmp_lt_i32 s67, 0
	v_mov_b64_e32 v[154:155], s[16:17]
	s_movk_i32 s100, 0x0
	v_lshl_add_u64 v[122:123], v[224:225], 0, s[100:101]
	s_cselect_b64 s[6:7], -1, 0
	s_nop 0
	v_cvt_f32_i32_e32 v118, v118
	v_cvt_f32_i32_e32 v119, v119
	v_cvt_f32_i32_e32 v120, v120
	v_cvt_f32_i32_e32 v121, v121
	v_cvt_f32_i32_e32 v110, v110
	v_cvt_f32_i32_e32 v111, v111
	v_cvt_f32_i32_e32 v112, v112
	v_cvt_f32_i32_e32 v113, v113
	v_cvt_f32_i32_e32 v102, v102
	v_cvt_f32_i32_e32 v103, v103
	v_cvt_f32_i32_e32 v104, v104
	v_cvt_f32_i32_e32 v105, v105
	v_cvt_f32_i32_e32 v100, v100
	v_cvt_f32_i32_e32 v101, v101
	v_cvt_f32_i32_e32 v94, v94
	v_cvt_f32_i32_e32 v95, v95
	v_cvt_f32_i32_e32 v96, v96
	v_cvt_f32_i32_e32 v97, v97
	v_cvt_f32_i32_e32 v92, v92
	v_cvt_f32_i32_e32 v93, v93
	v_cvt_f32_i32_e32 v86, v86
	v_cvt_f32_i32_e32 v87, v87
	v_cvt_f32_i32_e32 v88, v88
	v_cvt_f32_i32_e32 v89, v89
	v_cvt_f32_i32_e32 v84, v84
	v_cvt_f32_i32_e32 v85, v85
	v_cvt_f32_i32_e32 v78, v78
	v_cvt_f32_i32_e32 v79, v79
	v_cvt_f32_i32_e32 v80, v80
	v_cvt_f32_i32_e32 v81, v81
	v_cvt_f32_i32_e32 v76, v76
	v_cvt_f32_i32_e32 v77, v77
	v_cvt_f32_i32_e32 v70, v70
	v_cvt_f32_i32_e32 v71, v71
	v_cvt_f32_i32_e32 v72, v72
	v_cvt_f32_i32_e32 v73, v73
	v_cvt_f32_i32_e32 v68, v68
	v_cvt_f32_i32_e32 v69, v69
	v_cvt_f32_i32_e32 v53, v53
	v_cvt_f32_i32_e32 v54, v54
	v_cvt_f32_i32_e32 v55, v55
	v_cvt_f32_i32_e32 v56, v56
	v_cvt_f32_i32_e32 v57, v57
	v_cvt_f32_i32_e32 v50, v50
	v_cvt_f32_i32_e32 v51, v51
	v_cvt_f32_i32_e32 v52, v52
	v_cvt_f32_i32_e32 v45, v45
	v_cvt_f32_i32_e32 v46, v46
	v_cvt_f32_i32_e32 v47, v47
	v_cvt_f32_i32_e32 v48, v48
	v_cvt_f32_i32_e32 v49, v49
	v_cvt_f32_i32_e32 v42, v42
	v_cvt_f32_i32_e32 v43, v43
	v_cvt_f32_i32_e32 v44, v44
	v_cvt_f32_i32_e32 v37, v37
	v_cvt_f32_i32_e32 v38, v38
	v_cvt_f32_i32_e32 v39, v39
	v_cvt_f32_i32_e32 v40, v40
	s_waitcnt vmcnt(0)
	s_mov_b32 s98, 0x3c3a1e78
	v_pk_mul_f32 v[126:127], v[168:169], s[98:99] op_sel_hi:[1,0]
	v_pk_mul_f32 v[156:157], v[160:161], s[98:99] op_sel_hi:[1,0]
	v_pk_mul_f32 v[160:161], v[158:159], s[98:99] op_sel_hi:[1,0]
	v_pk_mul_f32 v[158:159], v[166:167], s[98:99] op_sel_hi:[1,0]
	v_mul_f32_e32 v166, v160, v153
	v_mul_f32_e32 v167, v161, v153
	v_mul_f32_e32 v168, v156, v153
	v_mul_f32_e32 v169, v157, v153
	v_mul_f32_e32 v171, v153, v158
	v_mul_f32_e32 v180, v153, v159
	v_mul_f32_e32 v181, v153, v126
	v_mul_f32_e32 v153, v153, v127
	v_mul_f32_e32 v166, v166, v172
	v_mul_f32_e32 v167, v167, v173
	v_mul_f32_e32 v168, v168, v174
	v_mul_f32_e32 v169, v169, v175
	v_mul_f32_e32 v171, v171, v176
	v_mul_f32_e32 v172, v180, v177
	v_mul_f32_e32 v173, v181, v178
	v_mul_f32_e32 v153, v153, v179
	v_exp_f32_e64 v174, -v166
	v_exp_f32_e64 v175, -v167
	v_exp_f32_e64 v176, -v168
	v_exp_f32_e64 v177, -v169
	v_exp_f32_e64 v178, -v171
	v_exp_f32_e64 v179, -v172
	v_exp_f32_e64 v180, -v173
	v_exp_f32_e64 v181, -v153
	v_add_f32_e32 v174, 1.0, v174
	v_add_f32_e32 v175, 1.0, v175
	v_add_f32_e32 v176, 1.0, v176
	v_add_f32_e32 v177, 1.0, v177
	v_add_f32_e32 v178, 1.0, v178
	v_add_f32_e32 v179, 1.0, v179
	v_add_f32_e32 v180, 1.0, v180
	v_add_f32_e32 v181, 1.0, v181
	v_rcp_f32_e32 v174, v174
	v_rcp_f32_e32 v175, v175
	v_rcp_f32_e32 v176, v176
	v_rcp_f32_e32 v177, v177
	v_rcp_f32_e32 v178, v178
	v_rcp_f32_e32 v179, v179
	v_rcp_f32_e32 v180, v180
	v_rcp_f32_e32 v181, v181
	v_cvt_pk_bf16_f32 v166, v174, v175
	v_cvt_pk_bf16_f32 v167, v176, v177
	v_cvt_pk_bf16_f32 v168, v178, v179
	v_cvt_pk_bf16_f32 v169, v180, v181
	global_store_dwordx4 v[122:123], v[166:169], off
	s_nop 1
	v_cvt_f32_i32_e32 v171, v116
	v_cvt_f32_i32_e32 v168, v114
	v_cvt_f32_i32_e32 v169, v115
	v_cvt_f32_i32_e32 v172, v117
	v_or_b32_e32 v166, 32, v152
	v_ashrrev_i32_e32 v167, 31, v166
	s_movk_i32 s100, 0x800
	v_lshl_add_u64 v[114:115], v[224:225], 0, s[100:101]
	v_lshl_add_u64 v[116:117], v[166:167], 2, s[26:27]
	s_nop 0
	v_cvt_f32_i32_e32 v41, v41
	v_cvt_f32_i32_e32 v34, v34
	v_cvt_f32_i32_e32 v35, v35
	v_cvt_f32_i32_e32 v36, v36
	v_cvt_f32_i32_e32 v29, v29
	v_cvt_f32_i32_e32 v30, v30
	v_cvt_f32_i32_e32 v31, v31
	v_cvt_f32_i32_e32 v32, v32
	v_cvt_f32_i32_e32 v33, v33
	v_cvt_f32_i32_e32 v26, v26
	v_cvt_f32_i32_e32 v27, v27
	v_cvt_f32_i32_e32 v28, v28
	v_cvt_f32_i32_e32 v21, v21
	v_cvt_f32_i32_e32 v22, v22
	v_cvt_f32_i32_e32 v23, v23
	v_cvt_f32_i32_e32 v24, v24
	v_cvt_f32_i32_e32 v25, v25
	v_cvt_f32_i32_e32 v18, v18
	v_cvt_f32_i32_e32 v19, v19
	v_cvt_f32_i32_e32 v20, v20
	v_cvt_f32_i32_e32 v13, v13
	v_cvt_f32_i32_e32 v14, v14
	v_cvt_f32_i32_e32 v15, v15
	v_cvt_f32_i32_e32 v16, v16
	v_cvt_f32_i32_e32 v17, v17
	v_cvt_f32_i32_e32 v10, v10
	v_cvt_f32_i32_e32 v11, v11
	v_cvt_f32_i32_e32 v12, v12
	v_cvt_f32_i32_e32 v5, v5
	v_cvt_f32_i32_e32 v6, v6
	v_cvt_f32_i32_e32 v7, v7
	v_cvt_f32_i32_e32 v8, v8
	v_cvt_f32_i32_e32 v9, v9
	v_cvt_f32_i32_e32 v2, v2
	v_cvt_f32_i32_e32 v3, v3
	v_cvt_f32_i32_e32 v4, v4
	s_and_b64 vcc, exec, s[4:5]
	v_mov_b32_e32 v153, v192
	v_mul_f32_e32 v167, v160, v153
	v_mul_f32_e32 v170, v161, v153
	v_mul_f32_e32 v173, v156, v153
	v_mul_f32_e32 v174, v157, v153
	v_mul_f32_e32 v175, v158, v153
	v_mul_f32_e32 v176, v159, v153
	v_mul_f32_e32 v177, v126, v153
	v_mul_f32_e32 v153, v127, v153
	v_mul_f32_e32 v118, v167, v118
	v_mul_f32_e32 v119, v170, v119
	v_mul_f32_e32 v120, v173, v120
	v_mul_f32_e32 v121, v174, v121
	v_mul_f32_e32 v167, v175, v168
	v_mul_f32_e32 v168, v176, v169
	v_mul_f32_e32 v169, v177, v171
	v_mul_f32_e32 v153, v153, v172
	v_exp_f32_e64 v170, -v118
	v_exp_f32_e64 v171, -v119
	v_exp_f32_e64 v172, -v120
	v_exp_f32_e64 v173, -v121
	v_exp_f32_e64 v174, -v167
	v_exp_f32_e64 v175, -v168
	v_exp_f32_e64 v176, -v169
	v_exp_f32_e64 v177, -v153
	v_add_f32_e32 v170, 1.0, v170
	v_add_f32_e32 v171, 1.0, v171
	v_add_f32_e32 v172, 1.0, v172
	v_add_f32_e32 v173, 1.0, v173
	v_add_f32_e32 v174, 1.0, v174
	v_add_f32_e32 v175, 1.0, v175
	v_add_f32_e32 v176, 1.0, v176
	v_add_f32_e32 v177, 1.0, v177
	v_rcp_f32_e32 v170, v170
	v_rcp_f32_e32 v171, v171
	v_rcp_f32_e32 v172, v172
	v_rcp_f32_e32 v173, v173
	v_rcp_f32_e32 v174, v174
	v_rcp_f32_e32 v175, v175
	v_rcp_f32_e32 v176, v176
	v_rcp_f32_e32 v177, v177
	v_cvt_pk_bf16_f32 v118, v170, v171
	v_cvt_pk_bf16_f32 v119, v172, v173
	v_cvt_pk_bf16_f32 v120, v174, v175
	v_cvt_pk_bf16_f32 v121, v176, v177
	global_store_dwordx4 v[114:115], v[118:121], off
	s_nop 1
	v_cvt_f32_i32_e32 v153, v107
	v_cvt_f32_i32_e32 v121, v106
	v_cvt_f32_i32_e32 v167, v108
	v_cvt_f32_i32_e32 v168, v109
	v_or_b32_e32 v118, 48, v152
	v_ashrrev_i32_e32 v119, 31, v118
	s_movk_i32 s100, 0x1000
	v_lshl_add_u64 v[106:107], v[224:225], 0, s[100:101]
	v_lshl_add_u64 v[108:109], v[118:119], 2, s[26:27]
	s_nop 0
	v_mov_b32_e32 v120, v194
	v_mul_f32_e32 v119, v160, v120
	v_mul_f32_e32 v166, v161, v120
	v_mul_f32_e32 v169, v156, v120
	v_mul_f32_e32 v170, v157, v120
	v_mul_f32_e32 v171, v158, v120
	v_mul_f32_e32 v172, v159, v120
	v_mul_f32_e32 v173, v126, v120
	v_mul_f32_e32 v120, v127, v120
	v_mul_f32_e32 v110, v119, v110
	v_mul_f32_e32 v111, v166, v111
	v_mul_f32_e32 v112, v169, v112
	v_mul_f32_e32 v113, v170, v113
	v_mul_f32_e32 v119, v171, v121
	v_mul_f32_e32 v121, v172, v153
	v_mul_f32_e32 v153, v173, v167
	v_mul_f32_e32 v120, v120, v168
	v_exp_f32_e64 v166, -v110
	v_exp_f32_e64 v167, -v111
	v_exp_f32_e64 v168, -v112
	v_exp_f32_e64 v169, -v113
	v_exp_f32_e64 v170, -v119
	v_exp_f32_e64 v171, -v121
	v_exp_f32_e64 v172, -v153
	v_exp_f32_e64 v173, -v120
	v_add_f32_e32 v166, 1.0, v166
	v_add_f32_e32 v167, 1.0, v167
	v_add_f32_e32 v168, 1.0, v168
	v_add_f32_e32 v169, 1.0, v169
	v_add_f32_e32 v170, 1.0, v170
	v_add_f32_e32 v171, 1.0, v171
	v_add_f32_e32 v172, 1.0, v172
	v_add_f32_e32 v173, 1.0, v173
	v_rcp_f32_e32 v166, v166
	v_rcp_f32_e32 v167, v167
	v_rcp_f32_e32 v168, v168
	v_rcp_f32_e32 v169, v169
	v_rcp_f32_e32 v170, v170
	v_rcp_f32_e32 v171, v171
	v_rcp_f32_e32 v172, v172
	v_rcp_f32_e32 v173, v173
	v_cvt_pk_bf16_f32 v110, v166, v167
	v_cvt_pk_bf16_f32 v111, v168, v169
	v_cvt_pk_bf16_f32 v112, v170, v171
	v_cvt_pk_bf16_f32 v113, v172, v173
	global_store_dwordx4 v[106:107], v[110:113], off
	s_nop 1
	v_mov_b32_e32 v110, v196
	v_mul_f32_e32 v119, v156, v110
	v_cvt_f32_i32_e32 v111, v98
	v_cvt_f32_i32_e32 v112, v99
	s_movk_i32 s100, 0x1800
	v_lshl_add_u64 v[98:99], v[224:225], 0, s[100:101]
	v_mul_f32_e32 v113, v160, v110
	v_mul_f32_e32 v118, v161, v110
	v_mul_f32_e32 v120, v157, v110
	v_mul_f32_e32 v121, v158, v110
	v_mul_f32_e32 v153, v159, v110
	v_mul_f32_e32 v166, v126, v110
	v_mul_f32_e32 v110, v127, v110
	v_mul_f32_e32 v102, v113, v102
	v_mul_f32_e32 v103, v118, v103
	v_mul_f32_e32 v104, v119, v104
	v_mul_f32_e32 v105, v120, v105
	v_mul_f32_e32 v111, v121, v111
	v_mul_f32_e32 v112, v153, v112
	v_mul_f32_e32 v100, v166, v100
	v_mul_f32_e32 v101, v110, v101
	v_exp_f32_e64 v110, -v102
	v_exp_f32_e64 v113, -v103
	v_exp_f32_e64 v118, -v104
	v_exp_f32_e64 v119, -v105
	v_exp_f32_e64 v120, -v111
	v_exp_f32_e64 v121, -v112
	v_exp_f32_e64 v153, -v100
	v_exp_f32_e64 v166, -v101
	v_add_f32_e32 v110, 1.0, v110
	v_add_f32_e32 v113, 1.0, v113
	v_add_f32_e32 v118, 1.0, v118
	v_add_f32_e32 v119, 1.0, v119
	v_add_f32_e32 v120, 1.0, v120
	v_add_f32_e32 v121, 1.0, v121
	v_add_f32_e32 v153, 1.0, v153
	v_add_f32_e32 v166, 1.0, v166
	v_rcp_f32_e32 v110, v110
	v_rcp_f32_e32 v113, v113
	v_rcp_f32_e32 v118, v118
	v_rcp_f32_e32 v119, v119
	v_rcp_f32_e32 v120, v120
	v_rcp_f32_e32 v121, v121
	v_rcp_f32_e32 v153, v153
	v_rcp_f32_e32 v166, v166
	s_nop 0
	v_cvt_pk_bf16_f32 v100, v110, v113
	v_cvt_pk_bf16_f32 v101, v118, v119
	v_cvt_pk_bf16_f32 v102, v120, v121
	v_cvt_pk_bf16_f32 v103, v153, v166
	global_store_dwordx4 v[98:99], v[100:103], off
	s_nop 1
	v_mov_b32_e32 v100, v198
	v_mul_f32_e32 v104, v161, v100
	v_cvt_f32_i32_e32 v101, v90
	v_cvt_f32_i32_e32 v102, v91
	v_mul_f32_e32 v103, v160, v100
	v_mul_f32_e32 v105, v156, v100
	v_mul_f32_e32 v110, v157, v100
	v_mul_f32_e32 v111, v158, v100
	v_mul_f32_e32 v112, v159, v100
	v_mul_f32_e32 v113, v126, v100
	v_mul_f32_e32 v100, v127, v100
	v_mul_f32_e32 v94, v103, v94
	v_mul_f32_e32 v95, v104, v95
	v_mul_f32_e32 v96, v105, v96
	v_mul_f32_e32 v97, v110, v97
	v_mul_f32_e32 v101, v111, v101
	v_mul_f32_e32 v102, v112, v102
	v_mul_f32_e32 v92, v113, v92
	v_mul_f32_e32 v93, v100, v93
	v_exp_f32_e64 v100, -v94
	v_exp_f32_e64 v103, -v95
	v_exp_f32_e64 v104, -v96
	v_exp_f32_e64 v105, -v97
	v_exp_f32_e64 v110, -v101
	v_exp_f32_e64 v111, -v102
	v_exp_f32_e64 v112, -v92
	v_exp_f32_e64 v113, -v93
	v_add_f32_e32 v100, 1.0, v100
	v_add_f32_e32 v103, 1.0, v103
	v_add_f32_e32 v104, 1.0, v104
	v_add_f32_e32 v105, 1.0, v105
	v_add_f32_e32 v110, 1.0, v110
	v_add_f32_e32 v111, 1.0, v111
	v_add_f32_e32 v112, 1.0, v112
	v_add_f32_e32 v113, 1.0, v113
	v_rcp_f32_e32 v100, v100
	v_rcp_f32_e32 v103, v103
	v_rcp_f32_e32 v104, v104
	v_rcp_f32_e32 v105, v105
	v_rcp_f32_e32 v110, v110
	v_rcp_f32_e32 v111, v111
	v_rcp_f32_e32 v112, v112
	v_rcp_f32_e32 v113, v113
	v_add_u32_e32 v90, 0x80, v152
	s_movk_i32 s100, 0x2000
	v_lshl_add_u64 v[90:91], v[224:225], 0, s[100:101]
	s_nop 0
	v_cvt_pk_bf16_f32 v92, v100, v103
	v_cvt_pk_bf16_f32 v93, v104, v105
	v_cvt_pk_bf16_f32 v94, v110, v111
	v_cvt_pk_bf16_f32 v95, v112, v113
	global_store_dwordx4 v[90:91], v[92:95], off
	s_nop 1
	v_mov_b32_e32 v92, v200
	v_mul_f32_e32 v96, v161, v92
	v_cvt_f32_i32_e32 v93, v82
	v_cvt_f32_i32_e32 v94, v83
	v_mul_f32_e32 v95, v160, v92
	v_mul_f32_e32 v97, v156, v92
	v_mul_f32_e32 v100, v157, v92
	v_mul_f32_e32 v101, v158, v92
	v_mul_f32_e32 v102, v159, v92
	v_mul_f32_e32 v103, v126, v92
	v_mul_f32_e32 v92, v127, v92
	v_mul_f32_e32 v86, v95, v86
	v_mul_f32_e32 v87, v96, v87
	v_mul_f32_e32 v88, v97, v88
	v_mul_f32_e32 v89, v100, v89
	v_mul_f32_e32 v93, v101, v93
	v_mul_f32_e32 v94, v102, v94
	v_mul_f32_e32 v84, v103, v84
	v_mul_f32_e32 v85, v92, v85
	v_exp_f32_e64 v92, -v86
	v_exp_f32_e64 v95, -v87
	v_exp_f32_e64 v96, -v88
	v_exp_f32_e64 v97, -v89
	v_exp_f32_e64 v100, -v93
	v_exp_f32_e64 v101, -v94
	v_exp_f32_e64 v102, -v84
	v_exp_f32_e64 v103, -v85
	v_add_f32_e32 v92, 1.0, v92
	v_add_f32_e32 v95, 1.0, v95
	v_add_f32_e32 v96, 1.0, v96
	v_add_f32_e32 v97, 1.0, v97
	v_add_f32_e32 v100, 1.0, v100
	v_add_f32_e32 v101, 1.0, v101
	v_add_f32_e32 v102, 1.0, v102
	v_add_f32_e32 v103, 1.0, v103
	v_rcp_f32_e32 v92, v92
	v_rcp_f32_e32 v95, v95
	v_rcp_f32_e32 v96, v96
	v_rcp_f32_e32 v97, v97
	v_rcp_f32_e32 v100, v100
	v_rcp_f32_e32 v101, v101
	v_rcp_f32_e32 v102, v102
	v_rcp_f32_e32 v103, v103
	v_add_u32_e32 v82, 0x90, v152
	s_movk_i32 s100, 0x2800
	v_lshl_add_u64 v[82:83], v[224:225], 0, s[100:101]
	s_nop 0
	v_cvt_pk_bf16_f32 v84, v92, v95
	v_cvt_pk_bf16_f32 v85, v96, v97
	v_cvt_pk_bf16_f32 v86, v100, v101
	v_cvt_pk_bf16_f32 v87, v102, v103
	global_store_dwordx4 v[82:83], v[84:87], off
	s_nop 1
	v_mov_b32_e32 v84, v202
	v_mul_f32_e32 v88, v161, v84
	v_cvt_f32_i32_e32 v85, v74
	v_cvt_f32_i32_e32 v86, v75
	v_mul_f32_e32 v87, v160, v84
	v_mul_f32_e32 v89, v156, v84
	v_mul_f32_e32 v92, v157, v84
	v_mul_f32_e32 v93, v158, v84
	v_mul_f32_e32 v94, v159, v84
	v_mul_f32_e32 v95, v126, v84
	v_mul_f32_e32 v84, v127, v84
	v_mul_f32_e32 v78, v87, v78
	v_mul_f32_e32 v79, v88, v79
	v_mul_f32_e32 v80, v89, v80
	v_mul_f32_e32 v81, v92, v81
	v_mul_f32_e32 v85, v93, v85
	v_mul_f32_e32 v86, v94, v86
	v_mul_f32_e32 v76, v95, v76
	v_mul_f32_e32 v77, v84, v77
	v_exp_f32_e64 v84, -v78
	v_exp_f32_e64 v87, -v79
	v_exp_f32_e64 v88, -v80
	v_exp_f32_e64 v89, -v81
	v_exp_f32_e64 v92, -v85
	v_exp_f32_e64 v93, -v86
	v_exp_f32_e64 v94, -v76
	v_exp_f32_e64 v95, -v77
	v_add_f32_e32 v84, 1.0, v84
	v_add_f32_e32 v87, 1.0, v87
	v_add_f32_e32 v88, 1.0, v88
	v_add_f32_e32 v89, 1.0, v89
	v_add_f32_e32 v92, 1.0, v92
	v_add_f32_e32 v93, 1.0, v93
	v_add_f32_e32 v94, 1.0, v94
	v_add_f32_e32 v95, 1.0, v95
	v_rcp_f32_e32 v84, v84
	v_rcp_f32_e32 v87, v87
	v_rcp_f32_e32 v88, v88
	v_rcp_f32_e32 v89, v89
	v_rcp_f32_e32 v92, v92
	v_rcp_f32_e32 v93, v93
	v_rcp_f32_e32 v94, v94
	v_rcp_f32_e32 v95, v95
	v_add_u32_e32 v74, 0xa0, v152
	s_movk_i32 s100, 0x3000
	v_lshl_add_u64 v[74:75], v[224:225], 0, s[100:101]
	s_nop 0
	v_cvt_pk_bf16_f32 v76, v84, v87
	v_cvt_pk_bf16_f32 v77, v88, v89
	v_cvt_pk_bf16_f32 v78, v92, v93
	v_cvt_pk_bf16_f32 v79, v94, v95
	global_store_dwordx4 v[74:75], v[76:79], off
	s_nop 1
	v_cvt_f32_i32_e32 v88, v61
	v_cvt_f32_i32_e32 v77, v66
	v_cvt_f32_i32_e32 v78, v67
	v_add_u32_e32 v66, 0xb0, v152
	s_movk_i32 s100, 0x3800
	v_lshl_add_u64 v[66:67], v[224:225], 0, s[100:101]
	s_nop 0
	s_mov_b64 s[0:1], -1
	v_mov_b32_e32 v76, v204
	v_mul_f32_e32 v79, v160, v76
	v_mul_f32_e32 v80, v161, v76
	v_mul_f32_e32 v81, v156, v76
	v_mul_f32_e32 v84, v157, v76
	v_mul_f32_e32 v85, v158, v76
	v_mul_f32_e32 v86, v159, v76
	v_mul_f32_e32 v87, v126, v76
	v_mul_f32_e32 v76, v127, v76
	v_mul_f32_e32 v70, v79, v70
	v_mul_f32_e32 v71, v80, v71
	v_mul_f32_e32 v72, v81, v72
	v_mul_f32_e32 v73, v84, v73
	v_mul_f32_e32 v77, v85, v77
	v_mul_f32_e32 v78, v86, v78
	v_mul_f32_e32 v68, v87, v68
	v_mul_f32_e32 v69, v76, v69
	v_exp_f32_e64 v76, -v70
	v_exp_f32_e64 v79, -v71
	v_exp_f32_e64 v80, -v72
	v_exp_f32_e64 v81, -v73
	v_exp_f32_e64 v84, -v77
	v_exp_f32_e64 v85, -v78
	v_exp_f32_e64 v86, -v68
	v_exp_f32_e64 v87, -v69
	v_add_f32_e32 v76, 1.0, v76
	v_add_f32_e32 v79, 1.0, v79
	v_add_f32_e32 v80, 1.0, v80
	v_add_f32_e32 v81, 1.0, v81
	v_add_f32_e32 v84, 1.0, v84
	v_add_f32_e32 v85, 1.0, v85
	v_add_f32_e32 v86, 1.0, v86
	v_add_f32_e32 v87, 1.0, v87
	v_rcp_f32_e32 v76, v76
	v_rcp_f32_e32 v79, v79
	v_rcp_f32_e32 v80, v80
	v_rcp_f32_e32 v81, v81
	v_rcp_f32_e32 v84, v84
	v_rcp_f32_e32 v85, v85
	v_rcp_f32_e32 v86, v86
	v_rcp_f32_e32 v87, v87
	v_cvt_pk_bf16_f32 v68, v76, v79
	v_cvt_pk_bf16_f32 v69, v80, v81
	v_cvt_pk_bf16_f32 v70, v84, v85
	v_cvt_pk_bf16_f32 v71, v86, v87
	global_store_dwordx4 v[66:67], v[68:71], off
	s_nop 1
	s_nop 1
	v_cvt_f32_i32_e32 v73, v62
	v_cvt_f32_i32_e32 v80, v63
	v_cvt_f32_i32_e32 v81, v64
	v_cvt_f32_i32_e32 v84, v65
	v_cvt_f32_i32_e32 v85, v58
	v_cvt_f32_i32_e32 v86, v59
	v_cvt_f32_i32_e32 v87, v60
	v_pk_mul_f32 v[60:61], v[208:209], s[98:99] op_sel_hi:[1,0]
	v_pk_mul_f32 v[64:65], v[206:207], s[98:99] op_sel_hi:[1,0]
	v_pk_mul_f32 v[58:59], v[212:213], s[98:99] op_sel_hi:[1,0]
	v_pk_mul_f32 v[62:63], v[210:211], s[98:99] op_sel_hi:[1,0]
	v_mov_b32_e32 v72, v190
	v_mul_f32_e32 v68, v64, v72
	v_mul_f32_e32 v69, v65, v72
	v_mul_f32_e32 v70, v60, v72
	v_mul_f32_e32 v71, v61, v72
	v_mul_f32_e32 v76, v72, v62
	v_mul_f32_e32 v77, v72, v63
	v_mul_f32_e32 v78, v72, v58
	v_mul_f32_e32 v72, v72, v59
	v_mul_f32_e32 v68, v68, v73
	v_mul_f32_e32 v69, v69, v80
	v_mul_f32_e32 v70, v70, v81
	v_mul_f32_e32 v71, v71, v84
	v_mul_f32_e32 v73, v76, v85
	v_mul_f32_e32 v76, v77, v86
	v_mul_f32_e32 v77, v78, v87
	v_mul_f32_e32 v72, v72, v88
	v_exp_f32_e64 v78, -v68
	v_exp_f32_e64 v79, -v69
	v_exp_f32_e64 v80, -v70
	v_exp_f32_e64 v81, -v71
	v_exp_f32_e64 v84, -v73
	v_exp_f32_e64 v85, -v76
	v_exp_f32_e64 v86, -v77
	v_exp_f32_e64 v87, -v72
	v_add_f32_e32 v78, 1.0, v78
	v_add_f32_e32 v79, 1.0, v79
	v_add_f32_e32 v80, 1.0, v80
	v_add_f32_e32 v81, 1.0, v81
	v_add_f32_e32 v84, 1.0, v84
	v_add_f32_e32 v85, 1.0, v85
	v_add_f32_e32 v86, 1.0, v86
	v_add_f32_e32 v87, 1.0, v87
	v_rcp_f32_e32 v78, v78
	v_rcp_f32_e32 v79, v79
	v_rcp_f32_e32 v80, v80
	v_rcp_f32_e32 v81, v81
	v_rcp_f32_e32 v84, v84
	v_rcp_f32_e32 v85, v85
	v_rcp_f32_e32 v86, v86
	v_rcp_f32_e32 v87, v87
	v_cvt_pk_bf16_f32 v68, v78, v79
	v_cvt_pk_bf16_f32 v69, v80, v81
	v_cvt_pk_bf16_f32 v70, v84, v85
	v_cvt_pk_bf16_f32 v71, v86, v87
	global_store_dwordx4 v[122:123], v[68:71], off offset:1024
	s_nop 1
	v_mov_b32_e32 v68, v192
	v_mul_f32_e32 v72, v61, v68
	v_mul_f32_e32 v69, v64, v68
	v_mul_f32_e32 v70, v65, v68
	v_mul_f32_e32 v71, v60, v68
	v_mul_f32_e32 v73, v62, v68
	v_mul_f32_e32 v76, v63, v68
	v_mul_f32_e32 v77, v58, v68
	v_mul_f32_e32 v68, v59, v68
	v_mul_f32_e32 v53, v68, v53
	v_mul_f32_e32 v54, v69, v54
	v_mul_f32_e32 v55, v70, v55
	v_mul_f32_e32 v56, v71, v56
	v_mul_f32_e32 v57, v72, v57
	v_mul_f32_e32 v50, v73, v50
	v_mul_f32_e32 v51, v76, v51
	v_mul_f32_e32 v52, v77, v52
	v_exp_f32_e64 v77, -v53
	v_exp_f32_e64 v68, -v54
	v_exp_f32_e64 v69, -v55
	v_exp_f32_e64 v70, -v56
	v_exp_f32_e64 v71, -v57
	v_exp_f32_e64 v72, -v50
	v_exp_f32_e64 v73, -v51
	v_exp_f32_e64 v76, -v52
	v_add_f32_e32 v77, 1.0, v77
	v_add_f32_e32 v68, 1.0, v68
	v_add_f32_e32 v69, 1.0, v69
	v_add_f32_e32 v70, 1.0, v70
	v_add_f32_e32 v71, 1.0, v71
	v_add_f32_e32 v72, 1.0, v72
	v_add_f32_e32 v73, 1.0, v73
	v_add_f32_e32 v76, 1.0, v76
	v_rcp_f32_e32 v77, v77
	v_rcp_f32_e32 v68, v68
	v_rcp_f32_e32 v69, v69
	v_rcp_f32_e32 v70, v70
	v_rcp_f32_e32 v71, v71
	v_rcp_f32_e32 v72, v72
	v_rcp_f32_e32 v73, v73
	v_rcp_f32_e32 v76, v76
	v_cvt_pk_bf16_f32 v50, v68, v69
	v_cvt_pk_bf16_f32 v51, v70, v71
	v_cvt_pk_bf16_f32 v52, v72, v73
	v_cvt_pk_bf16_f32 v53, v76, v77
	global_store_dwordx4 v[114:115], v[50:53], off offset:1024
	s_nop 1
	v_mov_b32_e32 v50, v194
	v_mul_f32_e32 v54, v61, v50
	v_mul_f32_e32 v51, v64, v50
	v_mul_f32_e32 v52, v65, v50
	v_mul_f32_e32 v53, v60, v50
	v_mul_f32_e32 v55, v62, v50
	v_mul_f32_e32 v56, v63, v50
	v_mul_f32_e32 v57, v58, v50
	v_mul_f32_e32 v50, v59, v50
	v_mul_f32_e32 v45, v50, v45
	v_mul_f32_e32 v46, v51, v46
	v_mul_f32_e32 v47, v52, v47
	v_mul_f32_e32 v48, v53, v48
	v_mul_f32_e32 v49, v54, v49
	v_mul_f32_e32 v42, v55, v42
	v_mul_f32_e32 v43, v56, v43
	v_mul_f32_e32 v44, v57, v44
	v_exp_f32_e64 v57, -v45
	v_exp_f32_e64 v50, -v46
	v_exp_f32_e64 v51, -v47
	v_exp_f32_e64 v52, -v48
	v_exp_f32_e64 v53, -v49
	v_exp_f32_e64 v54, -v42
	v_exp_f32_e64 v55, -v43
	v_exp_f32_e64 v56, -v44
	v_add_f32_e32 v57, 1.0, v57
	v_add_f32_e32 v50, 1.0, v50
	v_add_f32_e32 v51, 1.0, v51
	v_add_f32_e32 v52, 1.0, v52
	v_add_f32_e32 v53, 1.0, v53
	v_add_f32_e32 v54, 1.0, v54
	v_add_f32_e32 v55, 1.0, v55
	v_add_f32_e32 v56, 1.0, v56
	v_rcp_f32_e32 v57, v57
	v_rcp_f32_e32 v50, v50
	v_rcp_f32_e32 v51, v51
	v_rcp_f32_e32 v52, v52
	v_rcp_f32_e32 v53, v53
	v_rcp_f32_e32 v54, v54
	v_rcp_f32_e32 v55, v55
	v_rcp_f32_e32 v56, v56
	v_cvt_pk_bf16_f32 v42, v50, v51
	v_cvt_pk_bf16_f32 v43, v52, v53
	v_cvt_pk_bf16_f32 v44, v54, v55
	v_cvt_pk_bf16_f32 v45, v56, v57
	global_store_dwordx4 v[106:107], v[42:45], off offset:1024
	s_nop 1
	v_mov_b32_e32 v42, v196
	v_mul_f32_e32 v46, v61, v42
	v_mul_f32_e32 v43, v64, v42
	v_mul_f32_e32 v44, v65, v42
	v_mul_f32_e32 v45, v60, v42
	v_mul_f32_e32 v47, v62, v42
	v_mul_f32_e32 v48, v63, v42
	v_mul_f32_e32 v49, v58, v42
	v_mul_f32_e32 v42, v59, v42
	v_mul_f32_e32 v37, v42, v37
	v_mul_f32_e32 v38, v43, v38
	v_mul_f32_e32 v39, v44, v39
	v_mul_f32_e32 v40, v45, v40
	v_mul_f32_e32 v41, v46, v41
	v_mul_f32_e32 v34, v47, v34
	v_mul_f32_e32 v35, v48, v35
	v_mul_f32_e32 v36, v49, v36
	v_exp_f32_e64 v49, -v37
	v_exp_f32_e64 v42, -v38
	v_exp_f32_e64 v43, -v39
	v_exp_f32_e64 v44, -v40
	v_exp_f32_e64 v45, -v41
	v_exp_f32_e64 v46, -v34
	v_exp_f32_e64 v47, -v35
	v_exp_f32_e64 v48, -v36
	v_add_f32_e32 v49, 1.0, v49
	v_add_f32_e32 v42, 1.0, v42
	v_add_f32_e32 v43, 1.0, v43
	v_add_f32_e32 v44, 1.0, v44
	v_add_f32_e32 v45, 1.0, v45
	v_add_f32_e32 v46, 1.0, v46
	v_add_f32_e32 v47, 1.0, v47
	v_add_f32_e32 v48, 1.0, v48
	v_rcp_f32_e32 v49, v49
	v_rcp_f32_e32 v42, v42
	v_rcp_f32_e32 v43, v43
	v_rcp_f32_e32 v44, v44
	v_rcp_f32_e32 v45, v45
	v_rcp_f32_e32 v46, v46
	v_rcp_f32_e32 v47, v47
	v_rcp_f32_e32 v48, v48
	v_cvt_pk_bf16_f32 v34, v42, v43
	v_cvt_pk_bf16_f32 v35, v44, v45
	v_cvt_pk_bf16_f32 v36, v46, v47
	v_cvt_pk_bf16_f32 v37, v48, v49
	global_store_dwordx4 v[98:99], v[34:37], off offset:1024
	s_nop 1
	v_mov_b32_e32 v34, v198
	v_mul_f32_e32 v38, v61, v34
	v_mul_f32_e32 v35, v64, v34
	v_mul_f32_e32 v36, v65, v34
	v_mul_f32_e32 v37, v60, v34
	v_mul_f32_e32 v39, v62, v34
	v_mul_f32_e32 v40, v63, v34
	v_mul_f32_e32 v41, v58, v34
	v_mul_f32_e32 v34, v59, v34
	v_mul_f32_e32 v29, v34, v29
	v_mul_f32_e32 v30, v35, v30
	v_mul_f32_e32 v31, v36, v31
	v_mul_f32_e32 v32, v37, v32
	v_mul_f32_e32 v33, v38, v33
	v_mul_f32_e32 v26, v39, v26
	v_mul_f32_e32 v27, v40, v27
	v_mul_f32_e32 v28, v41, v28
	v_exp_f32_e64 v41, -v29
	v_exp_f32_e64 v34, -v30
	v_exp_f32_e64 v35, -v31
	v_exp_f32_e64 v36, -v32
	v_exp_f32_e64 v37, -v33
	v_exp_f32_e64 v38, -v26
	v_exp_f32_e64 v39, -v27
	v_exp_f32_e64 v40, -v28
	v_add_f32_e32 v41, 1.0, v41
	v_add_f32_e32 v34, 1.0, v34
	v_add_f32_e32 v35, 1.0, v35
	v_add_f32_e32 v36, 1.0, v36
	v_add_f32_e32 v37, 1.0, v37
	v_add_f32_e32 v38, 1.0, v38
	v_add_f32_e32 v39, 1.0, v39
	v_add_f32_e32 v40, 1.0, v40
	v_rcp_f32_e32 v41, v41
	v_rcp_f32_e32 v34, v34
	v_rcp_f32_e32 v35, v35
	v_rcp_f32_e32 v36, v36
	v_rcp_f32_e32 v37, v37
	v_rcp_f32_e32 v38, v38
	v_rcp_f32_e32 v39, v39
	v_rcp_f32_e32 v40, v40
	v_cvt_pk_bf16_f32 v26, v34, v35
	v_cvt_pk_bf16_f32 v27, v36, v37
	v_cvt_pk_bf16_f32 v28, v38, v39
	v_cvt_pk_bf16_f32 v29, v40, v41
	global_store_dwordx4 v[90:91], v[26:29], off offset:1024
	s_nop 1
	v_mov_b32_e32 v26, v200
	v_mul_f32_e32 v30, v61, v26
	v_mul_f32_e32 v27, v64, v26
	v_mul_f32_e32 v28, v65, v26
	v_mul_f32_e32 v29, v60, v26
	v_mul_f32_e32 v31, v62, v26
	v_mul_f32_e32 v32, v63, v26
	v_mul_f32_e32 v33, v58, v26
	v_mul_f32_e32 v26, v59, v26
	v_mul_f32_e32 v21, v26, v21
	v_mul_f32_e32 v22, v27, v22
	v_mul_f32_e32 v23, v28, v23
	v_mul_f32_e32 v24, v29, v24
	v_mul_f32_e32 v25, v30, v25
	v_mul_f32_e32 v18, v31, v18
	v_mul_f32_e32 v19, v32, v19
	v_mul_f32_e32 v20, v33, v20
	v_exp_f32_e64 v33, -v21
	v_exp_f32_e64 v26, -v22
	v_exp_f32_e64 v27, -v23
	v_exp_f32_e64 v28, -v24
	v_exp_f32_e64 v29, -v25
	v_exp_f32_e64 v30, -v18
	v_exp_f32_e64 v31, -v19
	v_exp_f32_e64 v32, -v20
	v_add_f32_e32 v33, 1.0, v33
	v_add_f32_e32 v26, 1.0, v26
	v_add_f32_e32 v27, 1.0, v27
	v_add_f32_e32 v28, 1.0, v28
	v_add_f32_e32 v29, 1.0, v29
	v_add_f32_e32 v30, 1.0, v30
	v_add_f32_e32 v31, 1.0, v31
	v_add_f32_e32 v32, 1.0, v32
	v_rcp_f32_e32 v33, v33
	v_rcp_f32_e32 v26, v26
	v_rcp_f32_e32 v27, v27
	v_rcp_f32_e32 v28, v28
	v_rcp_f32_e32 v29, v29
	v_rcp_f32_e32 v30, v30
	v_rcp_f32_e32 v31, v31
	v_rcp_f32_e32 v32, v32
	v_cvt_pk_bf16_f32 v18, v26, v27
	v_cvt_pk_bf16_f32 v19, v28, v29
	v_cvt_pk_bf16_f32 v20, v30, v31
	v_cvt_pk_bf16_f32 v21, v32, v33
	global_store_dwordx4 v[82:83], v[18:21], off offset:1024
	s_nop 1
	v_mov_b32_e32 v18, v202
	v_mul_f32_e32 v22, v61, v18
	v_mul_f32_e32 v19, v64, v18
	v_mul_f32_e32 v20, v65, v18
	v_mul_f32_e32 v21, v60, v18
	v_mul_f32_e32 v23, v62, v18
	v_mul_f32_e32 v24, v63, v18
	v_mul_f32_e32 v25, v58, v18
	v_mul_f32_e32 v18, v59, v18
	v_mul_f32_e32 v13, v18, v13
	v_mul_f32_e32 v14, v19, v14
	v_mul_f32_e32 v15, v20, v15
	v_mul_f32_e32 v16, v21, v16
	v_mul_f32_e32 v17, v22, v17
	v_mul_f32_e32 v10, v23, v10
	v_mul_f32_e32 v11, v24, v11
	v_mul_f32_e32 v12, v25, v12
	v_exp_f32_e64 v25, -v13
	v_exp_f32_e64 v18, -v14
	v_exp_f32_e64 v19, -v15
	v_exp_f32_e64 v20, -v16
	v_exp_f32_e64 v21, -v17
	v_exp_f32_e64 v22, -v10
	v_exp_f32_e64 v23, -v11
	v_exp_f32_e64 v24, -v12
	v_add_f32_e32 v25, 1.0, v25
	v_add_f32_e32 v18, 1.0, v18
	v_add_f32_e32 v19, 1.0, v19
	v_add_f32_e32 v20, 1.0, v20
	v_add_f32_e32 v21, 1.0, v21
	v_add_f32_e32 v22, 1.0, v22
	v_add_f32_e32 v23, 1.0, v23
	v_add_f32_e32 v24, 1.0, v24
	v_rcp_f32_e32 v25, v25
	v_rcp_f32_e32 v18, v18
	v_rcp_f32_e32 v19, v19
	v_rcp_f32_e32 v20, v20
	v_rcp_f32_e32 v21, v21
	v_rcp_f32_e32 v22, v22
	v_rcp_f32_e32 v23, v23
	v_rcp_f32_e32 v24, v24
	v_cvt_pk_bf16_f32 v10, v18, v19
	v_cvt_pk_bf16_f32 v11, v20, v21
	v_cvt_pk_bf16_f32 v12, v22, v23
	v_cvt_pk_bf16_f32 v13, v24, v25
	global_store_dwordx4 v[74:75], v[10:13], off offset:1024
	s_nop 1
	v_mov_b32_e32 v10, v204
	v_mul_f32_e32 v14, v61, v10
	v_mul_f32_e32 v11, v64, v10
	v_mul_f32_e32 v12, v65, v10
	v_mul_f32_e32 v13, v60, v10
	v_mul_f32_e32 v15, v62, v10
	v_mul_f32_e32 v16, v63, v10
	v_mul_f32_e32 v17, v58, v10
	v_mul_f32_e32 v10, v59, v10
	v_mul_f32_e32 v5, v10, v5
	v_mul_f32_e32 v6, v11, v6
	v_mul_f32_e32 v7, v12, v7
	v_mul_f32_e32 v8, v13, v8
	v_mul_f32_e32 v9, v14, v9
	v_mul_f32_e32 v2, v15, v2
	v_mul_f32_e32 v3, v16, v3
	v_mul_f32_e32 v4, v17, v4
	v_exp_f32_e64 v17, -v5
	v_exp_f32_e64 v10, -v6
	v_exp_f32_e64 v11, -v7
	v_exp_f32_e64 v12, -v8
	v_exp_f32_e64 v13, -v9
	v_exp_f32_e64 v14, -v2
	v_exp_f32_e64 v15, -v3
	v_exp_f32_e64 v16, -v4
	v_add_f32_e32 v17, 1.0, v17
	v_add_f32_e32 v10, 1.0, v10
	v_add_f32_e32 v11, 1.0, v11
	v_add_f32_e32 v12, 1.0, v12
	v_add_f32_e32 v13, 1.0, v13
	v_add_f32_e32 v14, 1.0, v14
	v_add_f32_e32 v15, 1.0, v15
	v_add_f32_e32 v16, 1.0, v16
	v_rcp_f32_e32 v17, v17
	v_rcp_f32_e32 v10, v10
	v_rcp_f32_e32 v11, v11
	v_rcp_f32_e32 v12, v12
	v_rcp_f32_e32 v13, v13
	v_rcp_f32_e32 v14, v14
	v_rcp_f32_e32 v15, v15
	v_rcp_f32_e32 v16, v16
	v_cvt_pk_bf16_f32 v2, v10, v11
	v_cvt_pk_bf16_f32 v3, v12, v13
	v_cvt_pk_bf16_f32 v4, v14, v15
	v_cvt_pk_bf16_f32 v5, v16, v17
	global_store_dwordx4 v[66:67], v[2:5], off offset:1024
	s_cbranch_vccnz .LBB0_600
	s_andn2_b64 vcc, exec, s[10:11]
	s_cbranch_vccnz .LBB0_599
	s_barrier
	s_branch .LBB0_599

.LBB0_1187:
	s_lshl_b32 s100, s48, 5
	s_add_i32 s100, s100, s49
	s_lshl_b32 s100, s100, 3
	s_mov_b32 s101, 0x9000
	v_lshrrev_b32_e32 v224, 6, v0
	v_and_b32_e32 v225, 63, v0
	v_add_u32_e32 v224, s100, v224
	v_mul_lo_u32 v224, v224, s101
	v_lshl_add_u32 v224, v225, 4, v224
	v_mov_b32_e32 v225, 0
	v_lshl_add_u64 v[224:225], s[36:37], 0, v[224:225]
	s_mov_b32 s100, 0x5000
	s_mov_b32 s101, 0
	v_lshl_add_u64 v[224:225], v[224:225], 0, s[100:101]
	s_mov_b32 s100, 0x1000
	s_mov_b32 s101, 0
	v_lshl_add_u64 v[226:227], v[224:225], 0, s[100:101]
	v_lshl_add_u64 v[228:229], v[226:227], 0, s[100:101]
	v_lshl_add_u64 v[230:231], v[228:229], 0, s[100:101]
	s_mov_b32 s100, 0x480000
	v_lshl_add_u64 v[232:233], v[224:225], 0, s[100:101]
	v_lshl_add_u64 v[234:235], v[226:227], 0, s[100:101]
	v_lshl_add_u64 v[236:237], v[228:229], 0, s[100:101]
	v_lshl_add_u64 v[238:239], v[230:231], 0, s[100:101]
	v_mov_b32_e32 v131, v0
	s_cmp_lg_u32 s72, 0
	v_ashrrev_i32_e32 v130, 2, v131
	v_and_b32_e32 v130, 0xffffffc0, v130
	v_lshl_add_u32 v130, s48, 8, v130
	v_and_or_b32 v130, v131, 15, v130
	v_lshrrev_b32_e32 v131, 1, v131
	v_and_b32_e32 v131, 0x78, v131
	v_lshl_or_b32 v144, s49, 8, v131
	s_cselect_b64 s[48:49], -1, 0
	s_cmp_eq_u32 s72, 0
	v_ashrrev_i32_e32 v145, 31, v144
	v_ashrrev_i32_e32 v131, 31, v130
	v_mad_i64_i32 v[178:179], s[0:1], v130, s67, 0
	v_or_b32_e32 v142, 16, v130
	v_or_b32_e32 v174, 32, v130
	v_or_b32_e32 v172, 48, v130
	v_add_u32_e32 v170, 0x80, v130
	v_add_u32_e32 v168, 0x90, v130
	v_add_u32_e32 v166, 0xa0, v130
	v_add_u32_e32 v164, 0xb0, v130
	s_cbranch_scc1 .LBB0_1195
	v_lshl_add_u64 v[132:133], s[36:37], 0, v[178:179]
	v_lshlrev_b64 v[176:177], 1, v[144:145]
	v_lshl_add_u64 v[132:133], v[132:133], 0, v[176:177]
	v_add_co_u32_e32 v134, vcc, 0x7000, v132
	v_mov_b64_e32 v[180:181], s[36:37]
	s_nop 0
	v_addc_co_u32_e32 v135, vcc, 0, v133, vcc
	global_load_dwordx4 v[138:141], v[232:233], off nt
	v_lshl_add_u64 v[132:133], v[132:133], 0, s[40:41]
	global_load_dwordx4 v[182:185], v[232:233], off offset:1024 nt
	v_lshlrev_b64 v[130:131], 13, v[130:131]
	v_mad_i64_i32 v[132:133], s[0:1], v142, s67, v[180:181]
	v_lshl_add_u64 v[130:131], s[38:39], 0, v[130:131]
	v_lshl_add_u64 v[132:133], v[132:133], 0, v[176:177]
	v_lshl_add_u64 v[202:203], v[130:131], 0, v[176:177]
	v_lshl_add_u64 v[130:131], v[132:133], 0, s[40:41]
	v_add_co_u32_e32 v132, vcc, 0x7000, v132
	v_mad_i64_i32 v[134:135], s[0:1], v174, s67, v[180:181]
	s_nop 0
	v_addc_co_u32_e32 v133, vcc, 0, v133, vcc
	global_load_dwordx4 v[186:189], v[232:233], off offset:2048 nt
	global_load_dwordx4 v[190:193], v[232:233], off offset:3072 nt
	v_lshl_add_u64 v[134:135], v[134:135], 0, v[176:177]
	v_lshl_add_u64 v[198:199], v[134:135], 0, s[40:41]
	v_add_co_u32_e32 v134, vcc, 0x7000, v134
	v_mad_i64_i32 v[136:137], s[0:1], v172, s67, v[180:181]
	s_nop 0
	v_addc_co_u32_e32 v135, vcc, 0, v135, vcc
	global_load_dwordx4 v[194:197], v[234:235], off nt
	s_nop 0
	global_load_dwordx4 v[198:201], v[234:235], off offset:1024 nt
	v_lshl_add_u64 v[136:137], v[136:137], 0, v[176:177]
	v_add_co_u32_e32 v130, vcc, 0x7000, v136
	v_lshl_add_u64 v[204:205], v[136:137], 0, s[40:41]
	s_nop 0
	v_addc_co_u32_e32 v131, vcc, 0, v137, vcc
	global_load_dwordx4 v[134:137], v[234:235], off offset:2048 nt
	s_nop 0
	global_load_dwordx4 v[130:133], v[234:235], off offset:3072 nt
	v_ashrrev_i32_e32 v143, 31, v142
	v_ashrrev_i32_e32 v175, 31, v174
	v_ashrrev_i32_e32 v173, 31, v172
	s_waitcnt vmcnt(0)
	v_lshlrev_b32_e32 v165, 16, v138
	v_and_b32_e32 v138, 0xffff0000, v138
	v_lshlrev_b32_e32 v167, 16, v139
	v_and_b32_e32 v139, 0xffff0000, v139
	v_lshlrev_b32_e32 v169, 16, v140
	v_and_b32_e32 v140, 0xffff0000, v140
	v_lshlrev_b32_e32 v171, 16, v141
	v_and_b32_e32 v141, 0xffff0000, v141
	v_max_f32_e32 v138, v138, v138
	v_max_f32_e32 v139, v139, v139
	v_max_f32_e32 v165, v165, v165
	v_max_f32_e32 v167, v167, v167
	v_max_f32_e32 v140, v140, v140
	v_max_f32_e32 v141, v141, v141
	v_max_f32_e32 v138, 0x358637bd, v138
	v_max_f32_e32 v139, 0x358637bd, v139
	v_max_f32_e32 v169, v169, v169
	v_max_f32_e32 v171, v171, v171
	v_max_f32_e32 v165, 0x358637bd, v165
	v_max_f32_e32 v167, 0x358637bd, v167
	v_max_f32_e32 v140, 0x358637bd, v140
	v_max_f32_e32 v141, 0x358637bd, v141
	v_mul_f32_e32 v138, v127, v138
	v_mul_f32_e32 v139, v129, v139
	v_max_f32_e32 v169, 0x358637bd, v169
	v_max_f32_e32 v171, 0x358637bd, v171
	v_mul_f32_e32 v165, v126, v165
	v_mul_f32_e32 v167, v128, v167
	v_mul_f32_e32 v140, v123, v140
	v_mul_f32_e32 v141, v125, v141
	v_cvt_pk_bf16_f32 v138, v165, v138
	v_cvt_pk_bf16_f32 v139, v167, v139
	v_lshlrev_b32_e32 v204, 16, v182
	v_mul_f32_e32 v169, v122, v169
	v_mul_f32_e32 v171, v124, v171
	v_cvt_pk_bf16_f32 v140, v169, v140
	v_cvt_pk_bf16_f32 v141, v171, v141
	global_store_dwordx4 v[202:203], v[138:141], off
	v_max_f32_e32 v204, v204, v204
	v_and_b32_e32 v165, 0xffff0000, v185
	v_and_b32_e32 v139, 0xffff0000, v182
	v_max_f32_e32 v139, v139, v139
	v_max_f32_e32 v138, 0x358637bd, v204
	v_max_f32_e32 v139, 0x358637bd, v139
	v_mul_f32_e32 v138, v94, v138
	v_mul_f32_e32 v139, v95, v139
	v_cvt_pk_bf16_f32 v138, v138, v139
	v_lshlrev_b32_e32 v139, 16, v183
	v_and_b32_e32 v140, 0xffff0000, v183
	v_max_f32_e32 v139, v139, v139
	v_max_f32_e32 v140, v140, v140
	v_max_f32_e32 v139, 0x358637bd, v139
	v_max_f32_e32 v140, 0x358637bd, v140
	v_mul_f32_e32 v139, v96, v139
	v_mul_f32_e32 v140, v97, v140
	v_cvt_pk_bf16_f32 v139, v139, v140
	v_lshlrev_b32_e32 v140, 16, v184
	v_and_b32_e32 v141, 0xffff0000, v184
	v_max_f32_e32 v140, v140, v140
	v_max_f32_e32 v141, v141, v141
	v_max_f32_e32 v140, 0x358637bd, v140
	v_max_f32_e32 v141, 0x358637bd, v141
	v_mul_f32_e32 v140, v90, v140
	v_mul_f32_e32 v141, v91, v141
	v_cvt_pk_bf16_f32 v140, v140, v141
	v_lshlrev_b32_e32 v141, 16, v185
	v_max_f32_e32 v141, v141, v141
	v_max_f32_e32 v141, 0x358637bd, v141
	v_max_f32_e32 v165, v165, v165
	v_mul_f32_e32 v141, v92, v141
	v_max_f32_e32 v165, 0x358637bd, v165
	v_mul_f32_e32 v165, v93, v165
	v_cvt_pk_bf16_f32 v141, v141, v165
	global_store_dwordx4 v[202:203], v[138:141], off offset:256
	v_and_b32_e32 v165, 0xffff0000, v189
	v_lshlrev_b64 v[182:183], 13, v[142:143]
	v_lshlrev_b32_e32 v138, 16, v186
	v_and_b32_e32 v139, 0xffff0000, v186
	v_max_f32_e32 v138, v138, v138
	v_max_f32_e32 v139, v139, v139
	v_max_f32_e32 v138, 0x358637bd, v138
	v_max_f32_e32 v139, 0x358637bd, v139
	v_mul_f32_e32 v138, v118, v138
	v_mul_f32_e32 v139, v119, v139
	v_cvt_pk_bf16_f32 v138, v138, v139
	v_lshlrev_b32_e32 v139, 16, v187
	v_and_b32_e32 v140, 0xffff0000, v187
	v_max_f32_e32 v139, v139, v139
	v_max_f32_e32 v140, v140, v140
	v_max_f32_e32 v139, 0x358637bd, v139
	v_max_f32_e32 v140, 0x358637bd, v140
	v_mul_f32_e32 v139, v120, v139
	v_mul_f32_e32 v140, v121, v140
	v_cvt_pk_bf16_f32 v139, v139, v140
	v_lshlrev_b32_e32 v140, 16, v188
	v_and_b32_e32 v141, 0xffff0000, v188
	v_max_f32_e32 v140, v140, v140
	v_max_f32_e32 v141, v141, v141
	v_max_f32_e32 v140, 0x358637bd, v140
	v_max_f32_e32 v141, 0x358637bd, v141
	v_mul_f32_e32 v140, v114, v140
	v_mul_f32_e32 v141, v115, v141
	v_cvt_pk_bf16_f32 v140, v140, v141
	v_lshlrev_b32_e32 v141, 16, v189
	v_max_f32_e32 v141, v141, v141
	v_max_f32_e32 v141, 0x358637bd, v141
	v_max_f32_e32 v165, v165, v165
	v_lshl_add_u64 v[182:183], s[38:39], 0, v[182:183]
	v_mul_f32_e32 v141, v116, v141
	v_max_f32_e32 v165, 0x358637bd, v165
	v_lshl_add_u64 v[182:183], v[182:183], 0, v[176:177]
	v_mul_f32_e32 v165, v117, v165
	v_cvt_pk_bf16_f32 v141, v141, v165
	global_store_dwordx4 v[182:183], v[138:141], off
	v_and_b32_e32 v143, 0xffff0000, v193
	v_max_f32_e32 v143, v143, v143
	v_lshlrev_b32_e32 v138, 16, v190
	v_and_b32_e32 v139, 0xffff0000, v190
	v_max_f32_e32 v138, v138, v138
	v_max_f32_e32 v139, v139, v139
	v_max_f32_e32 v138, 0x358637bd, v138
	v_max_f32_e32 v139, 0x358637bd, v139
	v_mul_f32_e32 v138, v86, v138
	v_mul_f32_e32 v139, v87, v139
	v_cvt_pk_bf16_f32 v138, v138, v139
	v_lshlrev_b32_e32 v139, 16, v191
	v_and_b32_e32 v140, 0xffff0000, v191
	v_max_f32_e32 v139, v139, v139
	v_max_f32_e32 v140, v140, v140
	v_max_f32_e32 v139, 0x358637bd, v139
	v_max_f32_e32 v140, 0x358637bd, v140
	v_mul_f32_e32 v139, v88, v139
	v_mul_f32_e32 v140, v89, v140
	v_cvt_pk_bf16_f32 v139, v139, v140
	v_lshlrev_b32_e32 v140, 16, v192
	v_and_b32_e32 v141, 0xffff0000, v192
	v_max_f32_e32 v140, v140, v140
	v_max_f32_e32 v141, v141, v141
	v_max_f32_e32 v140, 0x358637bd, v140
	v_max_f32_e32 v141, 0x358637bd, v141
	v_mul_f32_e32 v140, v82, v140
	v_mul_f32_e32 v141, v83, v141
	v_cvt_pk_bf16_f32 v140, v140, v141
	v_lshlrev_b32_e32 v141, 16, v193
	v_max_f32_e32 v141, v141, v141
	v_max_f32_e32 v141, 0x358637bd, v141
	v_mul_f32_e32 v141, v84, v141
	v_max_f32_e32 v143, 0x358637bd, v143
	v_mul_f32_e32 v143, v85, v143
	v_cvt_pk_bf16_f32 v141, v141, v143
	global_store_dwordx4 v[182:183], v[138:141], off offset:256
	v_and_b32_e32 v143, 0xffff0000, v197
	v_lshlrev_b64 v[182:183], 13, v[174:175]
	v_lshlrev_b32_e32 v138, 16, v194
	v_and_b32_e32 v139, 0xffff0000, v194
	v_max_f32_e32 v138, v138, v138
	v_max_f32_e32 v139, v139, v139
	v_max_f32_e32 v138, 0x358637bd, v138
	v_max_f32_e32 v139, 0x358637bd, v139
	v_mul_f32_e32 v138, v110, v138
	v_mul_f32_e32 v139, v111, v139
	v_cvt_pk_bf16_f32 v138, v138, v139
	v_lshlrev_b32_e32 v139, 16, v195
	v_and_b32_e32 v140, 0xffff0000, v195
	v_max_f32_e32 v139, v139, v139
	v_max_f32_e32 v140, v140, v140
	v_max_f32_e32 v139, 0x358637bd, v139
	v_max_f32_e32 v140, 0x358637bd, v140
	v_mul_f32_e32 v139, v112, v139
	v_mul_f32_e32 v140, v113, v140
	v_cvt_pk_bf16_f32 v139, v139, v140
	v_lshlrev_b32_e32 v140, 16, v196
	v_and_b32_e32 v141, 0xffff0000, v196
	v_max_f32_e32 v140, v140, v140
	v_max_f32_e32 v141, v141, v141
	v_max_f32_e32 v140, 0x358637bd, v140
	v_max_f32_e32 v141, 0x358637bd, v141
	v_mul_f32_e32 v140, v106, v140
	v_mul_f32_e32 v141, v107, v141
	v_cvt_pk_bf16_f32 v140, v140, v141
	v_lshlrev_b32_e32 v141, 16, v197
	v_max_f32_e32 v141, v141, v141
	v_max_f32_e32 v141, 0x358637bd, v141
	v_max_f32_e32 v143, v143, v143
	v_lshl_add_u64 v[182:183], s[38:39], 0, v[182:183]
	v_mul_f32_e32 v141, v108, v141
	v_max_f32_e32 v143, 0x358637bd, v143
	v_lshl_add_u64 v[182:183], v[182:183], 0, v[176:177]
	v_mul_f32_e32 v143, v109, v143
	v_cvt_pk_bf16_f32 v141, v141, v143
	global_store_dwordx4 v[182:183], v[138:141], off
	v_and_b32_e32 v143, 0xffff0000, v201
	v_max_f32_e32 v143, v143, v143
	v_lshlrev_b32_e32 v138, 16, v198
	v_and_b32_e32 v139, 0xffff0000, v198
	v_max_f32_e32 v138, v138, v138
	v_max_f32_e32 v139, v139, v139
	v_max_f32_e32 v138, 0x358637bd, v138
	v_max_f32_e32 v139, 0x358637bd, v139
	v_mul_f32_e32 v138, v78, v138
	v_mul_f32_e32 v139, v79, v139
	v_cvt_pk_bf16_f32 v138, v138, v139
	v_lshlrev_b32_e32 v139, 16, v199
	v_and_b32_e32 v140, 0xffff0000, v199
	v_max_f32_e32 v139, v139, v139
	v_max_f32_e32 v140, v140, v140
	v_max_f32_e32 v139, 0x358637bd, v139
	v_max_f32_e32 v140, 0x358637bd, v140
	v_mul_f32_e32 v139, v80, v139
	v_mul_f32_e32 v140, v81, v140
	v_cvt_pk_bf16_f32 v139, v139, v140
	v_lshlrev_b32_e32 v140, 16, v200
	v_and_b32_e32 v141, 0xffff0000, v200
	v_max_f32_e32 v140, v140, v140
	v_max_f32_e32 v141, v141, v141
	v_max_f32_e32 v140, 0x358637bd, v140
	v_max_f32_e32 v141, 0x358637bd, v141
	v_mul_f32_e32 v140, v74, v140
	v_mul_f32_e32 v141, v75, v141
	v_cvt_pk_bf16_f32 v140, v140, v141
	v_lshlrev_b32_e32 v141, 16, v201
	v_max_f32_e32 v141, v141, v141
	v_max_f32_e32 v141, 0x358637bd, v141
	v_mul_f32_e32 v141, v76, v141
	v_max_f32_e32 v143, 0x358637bd, v143
	v_mul_f32_e32 v143, v77, v143
	v_cvt_pk_bf16_f32 v141, v141, v143
	global_store_dwordx4 v[182:183], v[138:141], off offset:256
	v_ashrrev_i32_e32 v171, 31, v170
	v_ashrrev_i32_e32 v169, 31, v168
	v_lshlrev_b32_e32 v138, 16, v134
	v_and_b32_e32 v134, 0xffff0000, v134
	v_max_f32_e32 v138, v138, v138
	v_max_f32_e32 v134, v134, v134
	v_max_f32_e32 v138, 0x358637bd, v138
	v_max_f32_e32 v134, 0x358637bd, v134
	v_mul_f32_e32 v138, v102, v138
	v_mul_f32_e32 v134, v103, v134
	v_cvt_pk_bf16_f32 v134, v138, v134
	v_lshlrev_b32_e32 v138, 16, v135
	v_and_b32_e32 v135, 0xffff0000, v135
	v_max_f32_e32 v138, v138, v138
	v_max_f32_e32 v135, v135, v135
	v_max_f32_e32 v138, 0x358637bd, v138
	v_max_f32_e32 v135, 0x358637bd, v135
	v_mul_f32_e32 v138, v104, v138
	v_mul_f32_e32 v135, v105, v135
	v_cvt_pk_bf16_f32 v135, v138, v135
	v_lshlrev_b32_e32 v138, 16, v136
	v_and_b32_e32 v136, 0xffff0000, v136
	v_max_f32_e32 v138, v138, v138
	v_max_f32_e32 v136, v136, v136
	v_max_f32_e32 v138, 0x358637bd, v138
	v_max_f32_e32 v136, 0x358637bd, v136
	v_mul_f32_e32 v138, v98, v138
	v_mul_f32_e32 v136, v99, v136
	v_cvt_pk_bf16_f32 v136, v138, v136
	v_lshlrev_b32_e32 v138, 16, v137
	v_and_b32_e32 v137, 0xffff0000, v137
	v_max_f32_e32 v138, v138, v138
	v_max_f32_e32 v137, v137, v137
	v_max_f32_e32 v138, 0x358637bd, v138
	v_max_f32_e32 v137, 0x358637bd, v137
	v_mul_f32_e32 v138, v100, v138
	v_mul_f32_e32 v137, v101, v137
	v_cvt_pk_bf16_f32 v137, v138, v137
	v_lshlrev_b64 v[138:139], 13, v[172:173]
	v_lshl_add_u64 v[138:139], s[38:39], 0, v[138:139]
	v_lshl_add_u64 v[138:139], v[138:139], 0, v[176:177]
	global_store_dwordx4 v[138:139], v[134:137], off
	v_ashrrev_i32_e32 v167, 31, v166
	v_ashrrev_i32_e32 v165, 31, v164
	v_lshlrev_b32_e32 v134, 16, v130
	v_and_b32_e32 v130, 0xffff0000, v130
	v_max_f32_e32 v134, v134, v134
	v_max_f32_e32 v130, v130, v130
	v_max_f32_e32 v134, 0x358637bd, v134
	v_max_f32_e32 v130, 0x358637bd, v130
	v_mul_f32_e32 v134, v70, v134
	v_mul_f32_e32 v130, v71, v130
	v_cvt_pk_bf16_f32 v130, v134, v130
	v_lshlrev_b32_e32 v134, 16, v131
	v_and_b32_e32 v131, 0xffff0000, v131
	v_max_f32_e32 v134, v134, v134
	v_max_f32_e32 v131, v131, v131
	v_max_f32_e32 v134, 0x358637bd, v134
	v_max_f32_e32 v131, 0x358637bd, v131
	v_mul_f32_e32 v134, v72, v134
	v_mul_f32_e32 v131, v73, v131
	v_cvt_pk_bf16_f32 v131, v134, v131
	v_lshlrev_b32_e32 v134, 16, v132
	v_and_b32_e32 v132, 0xffff0000, v132
	v_max_f32_e32 v134, v134, v134
	v_max_f32_e32 v132, v132, v132
	v_max_f32_e32 v134, 0x358637bd, v134
	v_max_f32_e32 v132, 0x358637bd, v132
	v_mul_f32_e32 v134, v66, v134
	v_mul_f32_e32 v132, v67, v132
	v_cvt_pk_bf16_f32 v132, v134, v132
	v_lshlrev_b32_e32 v134, 16, v133
	v_and_b32_e32 v133, 0xffff0000, v133
	v_max_f32_e32 v133, v133, v133
	v_max_f32_e32 v134, v134, v134
	v_max_f32_e32 v133, 0x358637bd, v133
	v_max_f32_e32 v134, 0x358637bd, v134
	v_mul_f32_e32 v133, v69, v133
	v_mul_f32_e32 v134, v68, v134
	v_cvt_pk_bf16_f32 v133, v134, v133
	global_store_dwordx4 v[138:139], v[130:133], off offset:256
	s_nop 1
	v_mad_i64_i32 v[130:131], s[0:1], v170, s67, v[180:181]
	v_lshl_add_u64 v[130:131], v[130:131], 0, v[176:177]
	v_add_co_u32_e32 v132, vcc, s68, v130
	s_nop 1
	v_addc_co_u32_e32 v133, vcc, 0, v131, vcc
	global_load_dwordx4 v[182:185], v[236:237], off nt
	v_lshl_add_u64 v[130:131], v[130:131], 0, s[40:41]
	global_load_dwordx4 v[186:189], v[236:237], off offset:1024 nt
	v_mad_i64_i32 v[130:131], s[0:1], v168, s67, v[180:181]
	v_lshl_add_u64 v[130:131], v[130:131], 0, v[176:177]
	v_lshl_add_u64 v[132:133], v[130:131], 0, s[40:41]
	v_add_co_u32_e32 v130, vcc, s68, v130
	s_waitcnt vmcnt(1)
	v_lshlrev_b32_e32 v143, 16, v182
	v_addc_co_u32_e32 v131, vcc, 0, v131, vcc
	global_load_dwordx4 v[190:193], v[236:237], off offset:2048 nt
	global_load_dwordx4 v[194:197], v[236:237], off offset:3072 nt
	v_mad_i64_i32 v[130:131], s[0:1], v166, s67, v[180:181]
	v_lshl_add_u64 v[130:131], v[130:131], 0, v[176:177]
	v_lshl_add_u64 v[132:133], v[130:131], 0, s[40:41]
	v_add_co_u32_e32 v130, vcc, s68, v130
	v_max_f32_e32 v143, v143, v143
	s_nop 0
	v_addc_co_u32_e32 v131, vcc, 0, v131, vcc
	global_load_dwordx4 v[198:201], v[238:239], off nt
	global_load_dwordx4 v[138:141], v[238:239], off offset:1024 nt
	v_mad_i64_i32 v[130:131], s[0:1], v164, s67, v[180:181]
	v_lshl_add_u64 v[130:131], v[130:131], 0, v[176:177]
	v_and_b32_e32 v173, 0xffff0000, v182
	v_lshl_add_u64 v[132:133], v[130:131], 0, s[40:41]
	v_add_co_u32_e32 v130, vcc, s68, v130
	v_max_f32_e32 v143, 0x358637bd, v143
	v_max_f32_e32 v173, v173, v173
	v_addc_co_u32_e32 v131, vcc, 0, v131, vcc
	v_mul_f32_e32 v143, v62, v143
	v_max_f32_e32 v173, 0x358637bd, v173
	global_load_dwordx4 v[134:137], v[238:239], off offset:2048 nt
	s_nop 0
	global_load_dwordx4 v[130:133], v[238:239], off offset:3072 nt
	v_mul_f32_e32 v173, v63, v173
	v_cvt_pk_bf16_f32 v180, v143, v173
	v_lshlrev_b32_e32 v143, 16, v183
	v_max_f32_e32 v143, v143, v143
	v_and_b32_e32 v173, 0xffff0000, v183
	v_max_f32_e32 v143, 0x358637bd, v143
	v_max_f32_e32 v173, v173, v173
	v_mul_f32_e32 v143, v64, v143
	v_max_f32_e32 v173, 0x358637bd, v173
	v_mul_f32_e32 v173, v65, v173
	v_cvt_pk_bf16_f32 v181, v143, v173
	v_lshlrev_b32_e32 v143, 16, v184
	v_max_f32_e32 v143, v143, v143
	v_and_b32_e32 v173, 0xffff0000, v184
	v_max_f32_e32 v143, 0x358637bd, v143
	v_max_f32_e32 v173, v173, v173
	v_mul_f32_e32 v143, v58, v143
	v_max_f32_e32 v173, 0x358637bd, v173
	v_mul_f32_e32 v173, v59, v173
	v_cvt_pk_bf16_f32 v182, v143, v173
	v_lshlrev_b32_e32 v143, 16, v185
	v_max_f32_e32 v143, v143, v143
	v_and_b32_e32 v173, 0xffff0000, v185
	v_max_f32_e32 v143, 0x358637bd, v143
	v_max_f32_e32 v173, v173, v173
	v_mul_f32_e32 v143, v60, v143
	v_max_f32_e32 v173, 0x358637bd, v173
	v_mul_f32_e32 v173, v61, v173
	v_cvt_pk_bf16_f32 v183, v143, v173
	s_waitcnt vmcnt(6)
	v_lshlrev_b32_e32 v143, 16, v186
	v_lshlrev_b64 v[184:185], 13, v[170:171]
	v_max_f32_e32 v143, v143, v143
	v_and_b32_e32 v171, 0xffff0000, v186
	v_lshl_add_u64 v[184:185], s[38:39], 0, v[184:185]
	v_max_f32_e32 v143, 0x358637bd, v143
	v_max_f32_e32 v171, v171, v171
	v_lshl_add_u64 v[184:185], v[184:185], 0, v[176:177]
	v_mul_f32_e32 v143, v30, v143
	v_max_f32_e32 v171, 0x358637bd, v171
	global_store_dwordx4 v[184:185], v[180:183], off
	v_mul_f32_e32 v171, v31, v171
	s_nop 0
	v_cvt_pk_bf16_f32 v180, v143, v171
	v_lshlrev_b32_e32 v143, 16, v187
	v_max_f32_e32 v143, v143, v143
	v_and_b32_e32 v171, 0xffff0000, v187
	v_max_f32_e32 v143, 0x358637bd, v143
	v_max_f32_e32 v171, v171, v171
	v_mul_f32_e32 v143, v32, v143
	v_max_f32_e32 v171, 0x358637bd, v171
	v_mul_f32_e32 v171, v33, v171
	v_cvt_pk_bf16_f32 v181, v143, v171
	v_lshlrev_b32_e32 v143, 16, v188
	v_max_f32_e32 v143, v143, v143
	v_and_b32_e32 v171, 0xffff0000, v188
	v_max_f32_e32 v143, 0x358637bd, v143
	v_max_f32_e32 v171, v171, v171
	v_mul_f32_e32 v143, v26, v143
	v_max_f32_e32 v171, 0x358637bd, v171
	v_mul_f32_e32 v171, v27, v171
	v_cvt_pk_bf16_f32 v182, v143, v171
	v_lshlrev_b32_e32 v143, 16, v189
	v_max_f32_e32 v143, v143, v143
	v_and_b32_e32 v171, 0xffff0000, v189
	v_max_f32_e32 v143, 0x358637bd, v143
	v_max_f32_e32 v171, v171, v171
	v_mul_f32_e32 v143, v28, v143
	v_max_f32_e32 v171, 0x358637bd, v171
	v_mul_f32_e32 v171, v29, v171
	v_cvt_pk_bf16_f32 v183, v143, v171
	s_waitcnt vmcnt(6)
	v_lshlrev_b32_e32 v143, 16, v190
	v_max_f32_e32 v143, v143, v143
	v_and_b32_e32 v171, 0xffff0000, v190
	v_max_f32_e32 v143, 0x358637bd, v143
	v_max_f32_e32 v171, v171, v171
	v_mul_f32_e32 v143, v54, v143
	v_max_f32_e32 v171, 0x358637bd, v171
	global_store_dwordx4 v[184:185], v[180:183], off offset:256
	v_mul_f32_e32 v171, v55, v171
	v_lshlrev_b64 v[184:185], 13, v[168:169]
	v_cvt_pk_bf16_f32 v180, v143, v171
	v_lshlrev_b32_e32 v143, 16, v191
	v_max_f32_e32 v143, v143, v143
	v_and_b32_e32 v171, 0xffff0000, v191
	v_max_f32_e32 v143, 0x358637bd, v143
	v_max_f32_e32 v171, v171, v171
	v_mul_f32_e32 v143, v56, v143
	v_max_f32_e32 v171, 0x358637bd, v171
	v_mul_f32_e32 v171, v57, v171
	v_cvt_pk_bf16_f32 v181, v143, v171
	v_lshlrev_b32_e32 v143, 16, v192
	v_max_f32_e32 v143, v143, v143
	v_and_b32_e32 v171, 0xffff0000, v192
	v_max_f32_e32 v143, 0x358637bd, v143
	v_max_f32_e32 v171, v171, v171
	v_mul_f32_e32 v143, v50, v143
	v_max_f32_e32 v171, 0x358637bd, v171
	v_mul_f32_e32 v171, v51, v171
	v_cvt_pk_bf16_f32 v182, v143, v171
	v_lshlrev_b32_e32 v143, 16, v193
	v_max_f32_e32 v143, v143, v143
	v_and_b32_e32 v171, 0xffff0000, v193
	v_max_f32_e32 v143, 0x358637bd, v143
	v_max_f32_e32 v171, v171, v171
	v_mul_f32_e32 v143, v52, v143
	v_max_f32_e32 v171, 0x358637bd, v171
	v_mul_f32_e32 v171, v53, v171
	v_cvt_pk_bf16_f32 v183, v143, v171
	s_waitcnt vmcnt(6)
	v_lshlrev_b32_e32 v143, 16, v194
	v_max_f32_e32 v143, v143, v143
	v_and_b32_e32 v169, 0xffff0000, v194
	v_lshl_add_u64 v[184:185], s[38:39], 0, v[184:185]
	v_max_f32_e32 v143, 0x358637bd, v143
	v_max_f32_e32 v169, v169, v169
	v_lshl_add_u64 v[184:185], v[184:185], 0, v[176:177]
	v_mul_f32_e32 v143, v22, v143
	v_max_f32_e32 v169, 0x358637bd, v169
	global_store_dwordx4 v[184:185], v[180:183], off
	v_mul_f32_e32 v169, v23, v169
	s_nop 0
	v_cvt_pk_bf16_f32 v180, v143, v169
	v_lshlrev_b32_e32 v143, 16, v195
	v_max_f32_e32 v143, v143, v143
	v_and_b32_e32 v169, 0xffff0000, v195
	v_max_f32_e32 v143, 0x358637bd, v143
	v_max_f32_e32 v169, v169, v169
	v_mul_f32_e32 v143, v24, v143
	v_max_f32_e32 v169, 0x358637bd, v169
	v_mul_f32_e32 v169, v25, v169
	v_cvt_pk_bf16_f32 v181, v143, v169
	v_lshlrev_b32_e32 v143, 16, v196
	v_max_f32_e32 v143, v143, v143
	v_and_b32_e32 v169, 0xffff0000, v196
	v_max_f32_e32 v143, 0x358637bd, v143
	v_max_f32_e32 v169, v169, v169
	v_mul_f32_e32 v143, v18, v143
	v_max_f32_e32 v169, 0x358637bd, v169
	v_mul_f32_e32 v169, v19, v169
	v_cvt_pk_bf16_f32 v182, v143, v169
	v_lshlrev_b32_e32 v143, 16, v197
	v_max_f32_e32 v143, v143, v143
	v_and_b32_e32 v169, 0xffff0000, v197
	v_max_f32_e32 v143, 0x358637bd, v143
	v_max_f32_e32 v169, v169, v169
	v_mul_f32_e32 v143, v20, v143
	v_max_f32_e32 v169, 0x358637bd, v169
	v_mul_f32_e32 v169, v21, v169
	v_cvt_pk_bf16_f32 v183, v143, v169
	s_waitcnt vmcnt(6)
	v_lshlrev_b32_e32 v143, 16, v198
	v_max_f32_e32 v143, v143, v143
	v_and_b32_e32 v169, 0xffff0000, v198
	v_max_f32_e32 v143, 0x358637bd, v143
	v_max_f32_e32 v169, v169, v169
	v_mul_f32_e32 v143, v46, v143
	v_max_f32_e32 v169, 0x358637bd, v169
	global_store_dwordx4 v[184:185], v[180:183], off offset:256
	v_mul_f32_e32 v169, v47, v169
	v_lshlrev_b64 v[184:185], 13, v[166:167]
	v_cvt_pk_bf16_f32 v180, v143, v169
	v_lshlrev_b32_e32 v143, 16, v199
	v_max_f32_e32 v143, v143, v143
	v_and_b32_e32 v169, 0xffff0000, v199
	v_max_f32_e32 v143, 0x358637bd, v143
	v_max_f32_e32 v169, v169, v169
	v_mul_f32_e32 v143, v48, v143
	v_max_f32_e32 v169, 0x358637bd, v169
	v_mul_f32_e32 v169, v49, v169
	v_cvt_pk_bf16_f32 v181, v143, v169
	v_lshlrev_b32_e32 v143, 16, v200
	v_max_f32_e32 v143, v143, v143
	v_and_b32_e32 v169, 0xffff0000, v200
	v_max_f32_e32 v143, 0x358637bd, v143
	v_max_f32_e32 v169, v169, v169
	v_mul_f32_e32 v143, v42, v143
	v_max_f32_e32 v169, 0x358637bd, v169
	v_mul_f32_e32 v169, v43, v169
	v_cvt_pk_bf16_f32 v182, v143, v169
	v_lshlrev_b32_e32 v143, 16, v201
	v_max_f32_e32 v143, v143, v143
	v_and_b32_e32 v169, 0xffff0000, v201
	v_max_f32_e32 v143, 0x358637bd, v143
	v_max_f32_e32 v169, v169, v169
	v_mul_f32_e32 v143, v44, v143
	v_max_f32_e32 v169, 0x358637bd, v169
	v_mul_f32_e32 v169, v45, v169
	v_cvt_pk_bf16_f32 v183, v143, v169
	s_waitcnt vmcnt(6)
	v_lshlrev_b32_e32 v143, 16, v138
	v_and_b32_e32 v138, 0xffff0000, v138
	v_max_f32_e32 v143, v143, v143
	v_max_f32_e32 v138, v138, v138
	v_lshl_add_u64 v[184:185], s[38:39], 0, v[184:185]
	v_max_f32_e32 v143, 0x358637bd, v143
	v_max_f32_e32 v138, 0x358637bd, v138
	v_lshl_add_u64 v[184:185], v[184:185], 0, v[176:177]
	v_mul_f32_e32 v143, v14, v143
	v_mul_f32_e32 v138, v15, v138
	global_store_dwordx4 v[184:185], v[180:183], off
	v_cvt_pk_bf16_f32 v138, v143, v138
	v_lshlrev_b32_e32 v143, 16, v139
	v_and_b32_e32 v139, 0xffff0000, v139
	v_max_f32_e32 v143, v143, v143
	v_max_f32_e32 v139, v139, v139
	v_max_f32_e32 v143, 0x358637bd, v143
	v_max_f32_e32 v139, 0x358637bd, v139
	v_mul_f32_e32 v143, v16, v143
	v_mul_f32_e32 v139, v17, v139
	v_cvt_pk_bf16_f32 v139, v143, v139
	v_lshlrev_b32_e32 v143, 16, v140
	v_and_b32_e32 v140, 0xffff0000, v140
	v_max_f32_e32 v143, v143, v143
	v_max_f32_e32 v140, v140, v140
	v_max_f32_e32 v143, 0x358637bd, v143
	v_max_f32_e32 v140, 0x358637bd, v140
	v_mul_f32_e32 v143, v10, v143
	v_mul_f32_e32 v140, v11, v140
	v_cvt_pk_bf16_f32 v140, v143, v140
	v_lshlrev_b32_e32 v143, 16, v141
	v_and_b32_e32 v141, 0xffff0000, v141
	v_max_f32_e32 v141, v141, v141
	v_max_f32_e32 v143, v143, v143
	v_max_f32_e32 v141, 0x358637bd, v141
	v_max_f32_e32 v143, 0x358637bd, v143
	v_mul_f32_e32 v141, v13, v141
	v_mul_f32_e32 v143, v12, v143
	v_cvt_pk_bf16_f32 v141, v143, v141
	global_store_dwordx4 v[184:185], v[138:141], off offset:256
	s_waitcnt vmcnt(7)
	s_nop 0
	v_lshlrev_b32_e32 v138, 16, v134
	v_and_b32_e32 v134, 0xffff0000, v134
	v_max_f32_e32 v138, v138, v138
	v_max_f32_e32 v134, v134, v134
	v_max_f32_e32 v138, 0x358637bd, v138
	v_max_f32_e32 v134, 0x358637bd, v134
	v_mul_f32_e32 v138, v38, v138
	v_mul_f32_e32 v134, v39, v134
	v_cvt_pk_bf16_f32 v134, v138, v134
	v_lshlrev_b32_e32 v138, 16, v135
	v_and_b32_e32 v135, 0xffff0000, v135
	v_max_f32_e32 v138, v138, v138
	v_max_f32_e32 v135, v135, v135
	v_max_f32_e32 v138, 0x358637bd, v138
	v_max_f32_e32 v135, 0x358637bd, v135
	v_mul_f32_e32 v138, v40, v138
	v_mul_f32_e32 v135, v41, v135
	v_cvt_pk_bf16_f32 v135, v138, v135
	v_lshlrev_b32_e32 v138, 16, v136
	v_and_b32_e32 v136, 0xffff0000, v136
	v_max_f32_e32 v138, v138, v138
	v_max_f32_e32 v136, v136, v136
	v_max_f32_e32 v138, 0x358637bd, v138
	v_max_f32_e32 v136, 0x358637bd, v136
	v_mul_f32_e32 v138, v34, v138
	v_mul_f32_e32 v136, v35, v136
	v_cvt_pk_bf16_f32 v136, v138, v136
	v_lshlrev_b32_e32 v138, 16, v137
	v_and_b32_e32 v137, 0xffff0000, v137
	v_max_f32_e32 v138, v138, v138
	v_max_f32_e32 v137, v137, v137
	v_max_f32_e32 v138, 0x358637bd, v138
	v_max_f32_e32 v137, 0x358637bd, v137
	v_mul_f32_e32 v138, v36, v138
	v_mul_f32_e32 v137, v37, v137
	v_cvt_pk_bf16_f32 v137, v138, v137
	v_lshlrev_b64 v[138:139], 13, v[164:165]
	v_lshl_add_u64 v[138:139], s[38:39], 0, v[138:139]
	v_lshl_add_u64 v[138:139], v[138:139], 0, v[176:177]
	global_store_dwordx4 v[138:139], v[134:137], off
	s_waitcnt vmcnt(7)
	s_nop 0
	v_lshlrev_b32_e32 v134, 16, v130
	v_and_b32_e32 v130, 0xffff0000, v130
	v_max_f32_e32 v134, v134, v134
	v_max_f32_e32 v130, v130, v130
	v_max_f32_e32 v134, 0x358637bd, v134
	v_max_f32_e32 v130, 0x358637bd, v130
	v_mul_f32_e32 v134, v6, v134
	v_mul_f32_e32 v130, v7, v130
	v_cvt_pk_bf16_f32 v130, v134, v130
	v_lshlrev_b32_e32 v134, 16, v131
	v_and_b32_e32 v131, 0xffff0000, v131
	v_max_f32_e32 v134, v134, v134
	v_max_f32_e32 v131, v131, v131
	v_max_f32_e32 v134, 0x358637bd, v134
	v_max_f32_e32 v131, 0x358637bd, v131
	v_mul_f32_e32 v134, v8, v134
	v_mul_f32_e32 v131, v9, v131
	v_cvt_pk_bf16_f32 v131, v134, v131
	v_lshlrev_b32_e32 v134, 16, v132
	v_and_b32_e32 v132, 0xffff0000, v132
	v_max_f32_e32 v134, v134, v134
	v_max_f32_e32 v132, v132, v132
	v_max_f32_e32 v134, 0x358637bd, v134
	v_max_f32_e32 v132, 0x358637bd, v132
	v_mul_f32_e32 v134, v2, v134
	v_mul_f32_e32 v132, v3, v132
	v_cvt_pk_bf16_f32 v132, v134, v132
	v_lshlrev_b32_e32 v134, 16, v133
	v_and_b32_e32 v133, 0xffff0000, v133
	v_max_f32_e32 v133, v133, v133
	v_max_f32_e32 v134, v134, v134
	v_max_f32_e32 v133, 0x358637bd, v133
	v_max_f32_e32 v134, 0x358637bd, v134
	v_mul_f32_e32 v133, v5, v133
	v_mul_f32_e32 v134, v4, v134
	v_cvt_pk_bf16_f32 v133, v134, v133
	global_store_dwordx4 v[138:139], v[130:133], off offset:256
	s_cbranch_execnz .LBB0_1190
.LBB0_1189:
	v_lshl_add_u64 v[176:177], v[144:145], 1, s[36:37]
	v_lshl_add_u64 v[130:131], v[176:177], 0, v[178:179]
	v_add_co_u32_e32 v132, vcc, 0x5000, v130
	s_nop 1
	v_addc_co_u32_e32 v133, vcc, 0, v131, vcc
	v_add_co_u32_e32 v130, vcc, 0x7000, v130
	global_load_dwordx4 v[178:181], v[224:225], off nt
	global_load_dwordx4 v[182:185], v[224:225], off offset:1024 nt
	v_addc_co_u32_e32 v131, vcc, 0, v131, vcc
	global_load_dwordx4 v[186:189], v[232:233], off nt
	global_load_dwordx4 v[190:193], v[232:233], off offset:1024 nt
	v_mad_i64_i32 v[130:131], s[0:1], v142, s67, v[176:177]
	v_add_co_u32_e32 v132, vcc, 0x5000, v130
	s_waitcnt vmcnt(0)
	v_lshlrev_b32_e32 v194, 16, v178
	v_addc_co_u32_e32 v133, vcc, 0, v131, vcc
	v_add_co_u32_e32 v134, vcc, s68, v130
	v_lshlrev_b32_e32 v169, 16, v187
	s_nop 0
	v_addc_co_u32_e32 v135, vcc, 0, v131, vcc
	global_load_dwordx4 v[138:141], v[224:225], off offset:2048 nt
	s_nop 0
	global_load_dwordx4 v[130:133], v[224:225], off offset:3072 nt
	s_nop 0
	global_load_dwordx4 v[142:145], v[232:233], off offset:2048 nt
	s_nop 0
	global_load_dwordx4 v[134:137], v[232:233], off offset:3072 nt
	v_and_b32_e32 v171, 0xffff0000, v187
	v_lshlrev_b32_e32 v198, 16, v182
	v_and_b32_e32 v199, 0xffff0000, v182
	v_lshlrev_b32_e32 v165, 16, v186
	v_and_b32_e32 v167, 0xffff0000, v186
	v_lshlrev_b32_e32 v173, 16, v188
	v_and_b32_e32 v175, 0xffff0000, v188
	v_lshlrev_b32_e32 v182, 16, v189
	v_and_b32_e32 v186, 0xffff0000, v189
	v_and_b32_e32 v188, 0xffff0000, v190
	v_lshlrev_b32_e32 v189, 16, v191
	v_max_f32_e32 v169, v169, v169
	v_max_f32_e32 v171, v171, v171
	v_max_f32_e32 v188, v188, v188
	v_max_f32_e32 v189, v189, v189
	v_max_f32_e32 v169, 0x358637bd, v169
	v_max_f32_e32 v171, 0x358637bd, v171
	v_max_f32_e32 v165, v165, v165
	v_max_f32_e32 v205, 0x358637bd, v188
	v_max_f32_e32 v206, 0x358637bd, v189
	v_rcp_f32_e32 v188, v169
	v_rcp_f32_e32 v189, v171
	v_max_f32_e32 v182, v182, v182
	v_max_f32_e32 v186, v186, v186
	v_max_f32_e32 v165, 0x358637bd, v165
	v_lshlrev_b32_e32 v187, 16, v190
	v_max_f32_e32 v182, 0x358637bd, v182
	v_max_f32_e32 v190, 0x358637bd, v186
	v_rcp_f32_e32 v186, v165
	v_and_b32_e32 v165, 0xffff0000, v191
	v_and_b32_e32 v195, 0xffff0000, v178
	v_lshlrev_b32_e32 v178, 16, v179
	v_and_b32_e32 v179, 0xffff0000, v179
	v_rcp_f32_e32 v202, v182
	v_rcp_f32_e32 v203, v190
	v_max_f32_e32 v165, v165, v165
	v_pk_mul_f32 v[178:179], v[188:189], v[178:179]
	v_max_f32_e32 v165, 0x358637bd, v165
	v_pk_mul_f32 v[128:129], v[128:129], v[178:179]
	v_rcp_f32_e32 v178, v206
	v_rcp_f32_e32 v179, v165
	v_lshlrev_b32_e32 v196, 16, v180
	v_and_b32_e32 v197, 0xffff0000, v180
	v_lshlrev_b32_e32 v180, 16, v181
	v_and_b32_e32 v181, 0xffff0000, v181
	v_lshlrev_b32_e32 v165, 16, v192
	v_pk_mul_f32 v[180:181], v[202:203], v[180:181]
	v_max_f32_e32 v165, v165, v165
	v_pk_mul_f32 v[124:125], v[124:125], v[180:181]
	v_lshlrev_b32_e32 v180, 16, v183
	v_and_b32_e32 v181, 0xffff0000, v183
	v_max_f32_e32 v165, 0x358637bd, v165
	v_pk_mul_f32 v[178:179], v[178:179], v[180:181]
	v_rcp_f32_e32 v180, v165
	v_and_b32_e32 v165, 0xffff0000, v192
	v_max_f32_e32 v165, v165, v165
	v_max_f32_e32 v165, 0x358637bd, v165
	v_rcp_f32_e32 v181, v165
	v_lshlrev_b32_e32 v165, 16, v193
	v_max_f32_e32 v165, v165, v165
	v_pk_mul_f32 v[96:97], v[96:97], v[178:179]
	v_lshlrev_b32_e32 v178, 16, v184
	v_and_b32_e32 v179, 0xffff0000, v184
	v_max_f32_e32 v165, 0x358637bd, v165
	v_pk_mul_f32 v[178:179], v[180:181], v[178:179]
	v_rcp_f32_e32 v180, v165
	v_and_b32_e32 v165, 0xffff0000, v193
	v_max_f32_e32 v165, v165, v165
	v_max_f32_e32 v165, 0x358637bd, v165
	v_rcp_f32_e32 v181, v165
	v_pk_mul_f32 v[90:91], v[90:91], v[178:179]
	v_lshlrev_b32_e32 v178, 16, v185
	v_and_b32_e32 v179, 0xffff0000, v185
	v_pk_mul_f32 v[178:179], v[180:181], v[178:179]
	v_max_f32_e32 v175, v175, v175
	v_pk_mul_f32 v[92:93], v[92:93], v[178:179]
	s_waitcnt vmcnt(3)
	v_lshlrev_b32_e32 v178, 16, v138
	v_and_b32_e32 v179, 0xffff0000, v138
	s_waitcnt vmcnt(1)
	v_lshlrev_b32_e32 v165, 16, v142
	v_and_b32_e32 v142, 0xffff0000, v142
	v_lshlrev_b32_e32 v138, 16, v143
	v_max_f32_e32 v142, v142, v142
	v_max_f32_e32 v138, v138, v138
	v_max_f32_e32 v142, 0x358637bd, v142
	v_max_f32_e32 v138, 0x358637bd, v138
	v_rcp_f32_e32 v181, v142
	v_rcp_f32_e32 v142, v138
	v_and_b32_e32 v138, 0xffff0000, v143
	v_max_f32_e32 v138, v138, v138
	v_max_f32_e32 v138, 0x358637bd, v138
	v_rcp_f32_e32 v143, v138
	v_lshlrev_b32_e32 v138, 16, v139
	v_and_b32_e32 v139, 0xffff0000, v139
	v_max_f32_e32 v165, v165, v165
	v_pk_mul_f32 v[138:139], v[142:143], v[138:139]
	v_lshlrev_b32_e32 v142, 16, v144
	v_and_b32_e32 v143, 0xffff0000, v144
	v_max_f32_e32 v142, v142, v142
	v_max_f32_e32 v143, v143, v143
	v_max_f32_e32 v142, 0x358637bd, v142
	v_max_f32_e32 v143, 0x358637bd, v143
	v_rcp_f32_e32 v142, v142
	v_rcp_f32_e32 v143, v143
	v_max_f32_e32 v165, 0x358637bd, v165
	v_rcp_f32_e32 v180, v165
	v_pk_mul_f32 v[120:121], v[120:121], v[138:139]
	v_lshlrev_b32_e32 v138, 16, v140
	v_and_b32_e32 v139, 0xffff0000, v140
	v_pk_mul_f32 v[138:139], v[142:143], v[138:139]
	v_mad_i64_i32 v[142:143], s[0:1], v174, s67, v[176:177]
	v_max_f32_e32 v175, 0x358637bd, v175
	v_add_co_u32_e32 v174, vcc, s68, v142
	v_rcp_f32_e32 v201, v175
	v_pk_mul_f32 v[178:179], v[180:181], v[178:179]
	v_addc_co_u32_e32 v175, vcc, 0, v143, vcc
	v_pk_mul_f32 v[118:119], v[118:119], v[178:179]
	global_load_dwordx4 v[178:181], v[234:235], off nt
	v_add_co_u32_e32 v142, vcc, s69, v142
	v_lshlrev_b32_e32 v140, 16, v145
	s_nop 0
	v_addc_co_u32_e32 v143, vcc, 0, v143, vcc
	global_load_dwordx4 v[182:185], v[226:227], off nt
	global_load_dwordx4 v[190:193], v[226:227], off offset:1024 nt
	v_max_f32_e32 v167, v167, v167
	v_max_f32_e32 v173, v173, v173
	v_max_f32_e32 v140, v140, v140
	v_max_f32_e32 v187, v187, v187
	v_max_f32_e32 v167, 0x358637bd, v167
	v_max_f32_e32 v173, 0x358637bd, v173
	v_max_f32_e32 v140, 0x358637bd, v140
	v_max_f32_e32 v204, 0x358637bd, v187
	v_rcp_f32_e32 v187, v167
	v_rcp_f32_e32 v200, v173
	v_rcp_f32_e32 v144, v140
	v_and_b32_e32 v140, 0xffff0000, v145
	v_max_f32_e32 v140, v140, v140
	v_max_f32_e32 v140, 0x358637bd, v140
	v_rcp_f32_e32 v145, v140
	v_pk_mul_f32 v[186:187], v[186:187], v[194:195]
	v_pk_mul_f32 v[188:189], v[200:201], v[196:197]
	v_pk_mul_f32 v[126:127], v[126:127], v[186:187]
	v_pk_mul_f32 v[122:123], v[122:123], v[188:189]
	global_load_dwordx4 v[186:189], v[234:235], off offset:1024 nt
	v_pk_mul_f32 v[114:115], v[114:115], v[138:139]
	v_lshlrev_b32_e32 v138, 16, v141
	v_and_b32_e32 v139, 0xffff0000, v141
	v_pk_mul_f32 v[138:139], v[144:145], v[138:139]
	s_waitcnt vmcnt(4)
	v_lshlrev_b32_e32 v140, 16, v134
	v_and_b32_e32 v134, 0xffff0000, v134
	v_pk_mul_f32 v[116:117], v[116:117], v[138:139]
	v_lshlrev_b32_e32 v138, 16, v130
	v_and_b32_e32 v139, 0xffff0000, v130
	v_lshlrev_b32_e32 v130, 16, v135
	v_max_f32_e32 v134, v134, v134
	v_max_f32_e32 v130, v130, v130
	v_max_f32_e32 v134, 0x358637bd, v134
	v_max_f32_e32 v130, 0x358637bd, v130
	v_rcp_f32_e32 v141, v134
	v_rcp_f32_e32 v134, v130
	v_and_b32_e32 v130, 0xffff0000, v135
	v_max_f32_e32 v130, v130, v130
	v_max_f32_e32 v130, 0x358637bd, v130
	v_rcp_f32_e32 v135, v130
	v_lshlrev_b32_e32 v130, 16, v131
	v_and_b32_e32 v131, 0xffff0000, v131
	v_max_f32_e32 v140, v140, v140
	v_pk_mul_f32 v[130:131], v[134:135], v[130:131]
	v_lshlrev_b32_e32 v134, 16, v136
	v_and_b32_e32 v135, 0xffff0000, v136
	v_max_f32_e32 v134, v134, v134
	v_max_f32_e32 v135, v135, v135
	v_max_f32_e32 v134, 0x358637bd, v134
	v_max_f32_e32 v135, 0x358637bd, v135
	v_rcp_f32_e32 v134, v134
	v_rcp_f32_e32 v135, v135
	v_pk_mul_f32 v[88:89], v[88:89], v[130:131]
	v_lshlrev_b32_e32 v130, 16, v132
	v_and_b32_e32 v131, 0xffff0000, v132
	v_lshlrev_b32_e32 v132, 16, v137
	v_max_f32_e32 v132, v132, v132
	v_max_f32_e32 v132, 0x358637bd, v132
	v_pk_mul_f32 v[130:131], v[134:135], v[130:131]
	v_rcp_f32_e32 v134, v132
	v_and_b32_e32 v132, 0xffff0000, v137
	v_max_f32_e32 v132, v132, v132
	v_max_f32_e32 v132, 0x358637bd, v132
	v_rcp_f32_e32 v135, v132
	v_pk_mul_f32 v[82:83], v[82:83], v[130:131]
	v_lshlrev_b32_e32 v130, 16, v133
	v_and_b32_e32 v131, 0xffff0000, v133
	v_max_f32_e32 v140, 0x358637bd, v140
	v_pk_mul_f32 v[130:131], v[134:135], v[130:131]
	v_rcp_f32_e32 v140, v140
	v_pk_mul_f32 v[84:85], v[84:85], v[130:131]
	v_mad_i64_i32 v[130:131], s[0:1], v172, s67, v[176:177]
	s_waitcnt vmcnt(3)
	v_lshlrev_b32_e32 v136, 16, v178
	v_max_f32_e32 v136, v136, v136
	v_add_co_u32_e32 v132, vcc, s69, v130
	v_max_f32_e32 v136, 0x358637bd, v136
	s_nop 0
	v_addc_co_u32_e32 v133, vcc, 0, v131, vcc
	v_rcp_f32_e32 v172, v136
	v_and_b32_e32 v136, 0xffff0000, v178
	v_add_co_u32_e32 v134, vcc, s68, v130
	v_max_f32_e32 v136, v136, v136
	v_pk_mul_f32 v[138:139], v[140:141], v[138:139]
	v_addc_co_u32_e32 v135, vcc, 0, v131, vcc
	v_max_f32_e32 v136, 0x358637bd, v136
	v_pk_mul_f32 v[86:87], v[86:87], v[138:139]
	global_load_dwordx4 v[138:141], v[226:227], off offset:2048 nt
	s_nop 0
	global_load_dwordx4 v[130:133], v[226:227], off offset:3072 nt
	v_rcp_f32_e32 v173, v136
	global_load_dwordx4 v[142:145], v[234:235], off offset:2048 nt
	s_nop 0
	global_load_dwordx4 v[134:137], v[234:235], off offset:3072 nt
	v_lshlrev_b32_e32 v165, 16, v179
	v_max_f32_e32 v165, v165, v165
	s_waitcnt vmcnt(6)
	v_lshlrev_b32_e32 v174, 16, v182
	v_and_b32_e32 v175, 0xffff0000, v182
	v_max_f32_e32 v165, 0x358637bd, v165
	v_pk_mul_f32 v[172:173], v[172:173], v[174:175]
	v_rcp_f32_e32 v174, v165
	v_and_b32_e32 v165, 0xffff0000, v179
	v_max_f32_e32 v165, v165, v165
	v_max_f32_e32 v165, 0x358637bd, v165
	v_rcp_f32_e32 v175, v165
	v_lshlrev_b32_e32 v165, 16, v180
	v_max_f32_e32 v165, v165, v165
	v_pk_mul_f32 v[110:111], v[110:111], v[172:173]
	v_lshlrev_b32_e32 v172, 16, v183
	v_and_b32_e32 v173, 0xffff0000, v183
	v_max_f32_e32 v165, 0x358637bd, v165
	v_pk_mul_f32 v[172:173], v[174:175], v[172:173]
	v_rcp_f32_e32 v174, v165
	v_and_b32_e32 v165, 0xffff0000, v180
	v_max_f32_e32 v165, v165, v165
	v_max_f32_e32 v165, 0x358637bd, v165
	v_rcp_f32_e32 v175, v165
	v_lshlrev_b32_e32 v165, 16, v181
	v_max_f32_e32 v165, v165, v165
	v_pk_mul_f32 v[112:113], v[112:113], v[172:173]
	v_lshlrev_b32_e32 v172, 16, v184
	v_and_b32_e32 v173, 0xffff0000, v184
	v_max_f32_e32 v165, 0x358637bd, v165
	v_pk_mul_f32 v[172:173], v[174:175], v[172:173]
	v_rcp_f32_e32 v174, v165
	v_and_b32_e32 v165, 0xffff0000, v181
	v_max_f32_e32 v165, v165, v165
	v_max_f32_e32 v165, 0x358637bd, v165
	v_rcp_f32_e32 v175, v165
	s_waitcnt vmcnt(4)
	v_lshlrev_b32_e32 v165, 16, v186
	v_max_f32_e32 v165, v165, v165
	v_pk_mul_f32 v[106:107], v[106:107], v[172:173]
	v_lshlrev_b32_e32 v172, 16, v185
	v_and_b32_e32 v173, 0xffff0000, v185
	v_max_f32_e32 v165, 0x358637bd, v165
	v_pk_mul_f32 v[172:173], v[174:175], v[172:173]
	v_rcp_f32_e32 v174, v165
	v_and_b32_e32 v165, 0xffff0000, v186
	v_max_f32_e32 v165, v165, v165
	v_max_f32_e32 v165, 0x358637bd, v165
	v_rcp_f32_e32 v175, v165
	v_lshlrev_b32_e32 v165, 16, v187
	v_max_f32_e32 v165, v165, v165
	v_pk_mul_f32 v[108:109], v[108:109], v[172:173]
	v_lshlrev_b32_e32 v172, 16, v190
	v_and_b32_e32 v173, 0xffff0000, v190
	v_max_f32_e32 v165, 0x358637bd, v165
	v_pk_mul_f32 v[172:173], v[174:175], v[172:173]
	v_rcp_f32_e32 v174, v165
	v_and_b32_e32 v165, 0xffff0000, v187
	v_max_f32_e32 v165, v165, v165
	v_max_f32_e32 v165, 0x358637bd, v165
	v_rcp_f32_e32 v175, v165
	v_lshlrev_b32_e32 v165, 16, v188
	v_max_f32_e32 v165, v165, v165
	v_pk_mul_f32 v[78:79], v[78:79], v[172:173]
	v_lshlrev_b32_e32 v172, 16, v191
	v_and_b32_e32 v173, 0xffff0000, v191
	v_max_f32_e32 v165, 0x358637bd, v165
	v_pk_mul_f32 v[172:173], v[174:175], v[172:173]
	v_rcp_f32_e32 v174, v165
	v_and_b32_e32 v165, 0xffff0000, v188
	v_max_f32_e32 v165, v165, v165
	v_max_f32_e32 v165, 0x358637bd, v165
	v_rcp_f32_e32 v175, v165
	v_lshlrev_b32_e32 v165, 16, v189
	v_max_f32_e32 v165, v165, v165
	v_pk_mul_f32 v[80:81], v[80:81], v[172:173]
	v_lshlrev_b32_e32 v172, 16, v192
	v_and_b32_e32 v173, 0xffff0000, v192
	v_max_f32_e32 v165, 0x358637bd, v165
	v_pk_mul_f32 v[172:173], v[174:175], v[172:173]
	v_rcp_f32_e32 v174, v165
	v_and_b32_e32 v165, 0xffff0000, v189
	v_max_f32_e32 v165, v165, v165
	v_max_f32_e32 v165, 0x358637bd, v165
	v_rcp_f32_e32 v175, v165
	v_pk_mul_f32 v[74:75], v[74:75], v[172:173]
	v_lshlrev_b32_e32 v172, 16, v193
	v_and_b32_e32 v173, 0xffff0000, v193
	v_pk_mul_f32 v[172:173], v[174:175], v[172:173]
	s_waitcnt vmcnt(1)
	v_lshlrev_b32_e32 v165, 16, v142
	v_and_b32_e32 v142, 0xffff0000, v142
	v_pk_mul_f32 v[76:77], v[76:77], v[172:173]
	v_lshlrev_b32_e32 v172, 16, v138
	v_and_b32_e32 v173, 0xffff0000, v138
	v_lshlrev_b32_e32 v138, 16, v143
	v_max_f32_e32 v142, v142, v142
	v_max_f32_e32 v138, v138, v138
	v_max_f32_e32 v142, 0x358637bd, v142
	v_max_f32_e32 v138, 0x358637bd, v138
	v_rcp_f32_e32 v175, v142
	v_rcp_f32_e32 v142, v138
	v_and_b32_e32 v138, 0xffff0000, v143
	v_max_f32_e32 v138, v138, v138
	v_max_f32_e32 v138, 0x358637bd, v138
	v_rcp_f32_e32 v143, v138
	v_lshlrev_b32_e32 v138, 16, v139
	v_and_b32_e32 v139, 0xffff0000, v139
	v_max_f32_e32 v165, v165, v165
	v_pk_mul_f32 v[138:139], v[142:143], v[138:139]
	v_lshlrev_b32_e32 v142, 16, v144
	v_and_b32_e32 v143, 0xffff0000, v144
	v_max_f32_e32 v142, v142, v142
	v_max_f32_e32 v143, v143, v143
	v_max_f32_e32 v142, 0x358637bd, v142
	v_max_f32_e32 v143, 0x358637bd, v143
	v_max_f32_e32 v165, 0x358637bd, v165
	v_rcp_f32_e32 v142, v142
	v_rcp_f32_e32 v143, v143
	v_rcp_f32_e32 v174, v165
	v_pk_mul_f32 v[104:105], v[104:105], v[138:139]
	v_lshlrev_b32_e32 v138, 16, v140
	v_and_b32_e32 v139, 0xffff0000, v140
	v_pk_mul_f32 v[138:139], v[142:143], v[138:139]
	v_mad_i64_i32 v[142:143], s[0:1], v170, s67, v[176:177]
	v_pk_mul_f32 v[172:173], v[174:175], v[172:173]
	v_add_co_u32_e32 v174, vcc, s68, v142
	v_pk_mul_f32 v[102:103], v[102:103], v[172:173]
	s_nop 0
	v_addc_co_u32_e32 v175, vcc, 0, v143, vcc
	global_load_dwordx4 v[170:173], v[236:237], off nt
	global_load_dwordx4 v[182:185], v[236:237], off offset:1024 nt
	v_add_co_u32_e32 v142, vcc, s69, v142
	v_lshlrev_b32_e32 v140, 16, v145
	s_nop 0
	v_addc_co_u32_e32 v143, vcc, 0, v143, vcc
	global_load_dwordx4 v[178:181], v[228:229], off nt
	global_load_dwordx4 v[186:189], v[228:229], off offset:1024 nt
	v_max_f32_e32 v140, v140, v140
	v_max_f32_e32 v140, 0x358637bd, v140
	v_rcp_f32_e32 v144, v140
	v_and_b32_e32 v140, 0xffff0000, v145
	v_max_f32_e32 v140, v140, v140
	v_max_f32_e32 v140, 0x358637bd, v140
	v_rcp_f32_e32 v145, v140
	v_pk_mul_f32 v[98:99], v[98:99], v[138:139]
	v_lshlrev_b32_e32 v138, 16, v141
	v_and_b32_e32 v139, 0xffff0000, v141
	v_pk_mul_f32 v[138:139], v[144:145], v[138:139]
	s_waitcnt vmcnt(4)
	v_lshlrev_b32_e32 v140, 16, v134
	v_and_b32_e32 v134, 0xffff0000, v134
	v_pk_mul_f32 v[100:101], v[100:101], v[138:139]
	v_lshlrev_b32_e32 v138, 16, v130
	v_and_b32_e32 v139, 0xffff0000, v130
	v_lshlrev_b32_e32 v130, 16, v135
	v_max_f32_e32 v134, v134, v134
	v_max_f32_e32 v130, v130, v130
	v_max_f32_e32 v134, 0x358637bd, v134
	v_max_f32_e32 v130, 0x358637bd, v130
	v_rcp_f32_e32 v141, v134
	v_rcp_f32_e32 v134, v130
	v_and_b32_e32 v130, 0xffff0000, v135
	v_max_f32_e32 v130, v130, v130
	v_max_f32_e32 v130, 0x358637bd, v130
	v_rcp_f32_e32 v135, v130
	v_lshlrev_b32_e32 v130, 16, v131
	v_and_b32_e32 v131, 0xffff0000, v131
	v_max_f32_e32 v140, v140, v140
	v_pk_mul_f32 v[130:131], v[134:135], v[130:131]
	v_lshlrev_b32_e32 v134, 16, v136
	v_and_b32_e32 v135, 0xffff0000, v136
	v_max_f32_e32 v134, v134, v134
	v_max_f32_e32 v135, v135, v135
	v_max_f32_e32 v134, 0x358637bd, v134
	v_max_f32_e32 v135, 0x358637bd, v135
	v_rcp_f32_e32 v134, v134
	v_rcp_f32_e32 v135, v135
	v_pk_mul_f32 v[72:73], v[72:73], v[130:131]
	v_lshlrev_b32_e32 v130, 16, v132
	v_and_b32_e32 v131, 0xffff0000, v132
	v_lshlrev_b32_e32 v132, 16, v137
	v_max_f32_e32 v132, v132, v132
	v_max_f32_e32 v132, 0x358637bd, v132
	v_pk_mul_f32 v[130:131], v[134:135], v[130:131]
	v_rcp_f32_e32 v134, v132
	v_and_b32_e32 v132, 0xffff0000, v137
	v_max_f32_e32 v132, v132, v132
	v_max_f32_e32 v132, 0x358637bd, v132
	v_rcp_f32_e32 v135, v132
	v_pk_mul_f32 v[66:67], v[66:67], v[130:131]
	v_lshlrev_b32_e32 v130, 16, v133
	v_and_b32_e32 v131, 0xffff0000, v133
	v_max_f32_e32 v140, 0x358637bd, v140
	v_pk_mul_f32 v[130:131], v[134:135], v[130:131]
	v_rcp_f32_e32 v140, v140
	v_pk_mul_f32 v[68:69], v[68:69], v[130:131]
	v_mad_i64_i32 v[130:131], s[0:1], v168, s67, v[176:177]
	v_add_co_u32_e32 v132, vcc, s69, v130
	v_pk_mul_f32 v[138:139], v[140:141], v[138:139]
	s_nop 0
	v_addc_co_u32_e32 v133, vcc, 0, v131, vcc
	v_add_co_u32_e32 v134, vcc, s68, v130
	v_pk_mul_f32 v[70:71], v[70:71], v[138:139]
	s_nop 0
	v_addc_co_u32_e32 v135, vcc, 0, v131, vcc
	global_load_dwordx4 v[138:141], v[228:229], off offset:2048 nt
	s_nop 0
	global_load_dwordx4 v[130:133], v[228:229], off offset:3072 nt
	s_waitcnt vmcnt(5)
	v_lshlrev_b32_e32 v136, 16, v170
	v_max_f32_e32 v136, v136, v136
	v_max_f32_e32 v136, 0x358637bd, v136
	v_rcp_f32_e32 v168, v136
	v_and_b32_e32 v136, 0xffff0000, v170
	v_max_f32_e32 v136, v136, v136
	v_max_f32_e32 v136, 0x358637bd, v136
	v_rcp_f32_e32 v169, v136
	global_load_dwordx4 v[142:145], v[236:237], off offset:2048 nt
	s_nop 0
	global_load_dwordx4 v[134:137], v[236:237], off offset:3072 nt
	v_lshlrev_b32_e32 v165, 16, v171
	v_max_f32_e32 v165, v165, v165
	v_max_f32_e32 v165, 0x358637bd, v165
	v_rcp_f32_e32 v170, v165
	v_and_b32_e32 v165, 0xffff0000, v171
	v_max_f32_e32 v165, v165, v165
	v_max_f32_e32 v165, 0x358637bd, v165
	v_rcp_f32_e32 v171, v165
	s_waitcnt vmcnt(5)
	v_lshlrev_b32_e32 v174, 16, v178
	v_and_b32_e32 v175, 0xffff0000, v178
	v_lshlrev_b32_e32 v165, 16, v172
	v_pk_mul_f32 v[168:169], v[168:169], v[174:175]
	v_max_f32_e32 v165, v165, v165
	v_pk_mul_f32 v[62:63], v[62:63], v[168:169]
	v_lshlrev_b32_e32 v168, 16, v179
	v_and_b32_e32 v169, 0xffff0000, v179
	v_max_f32_e32 v165, 0x358637bd, v165
	v_pk_mul_f32 v[168:169], v[170:171], v[168:169]
	v_rcp_f32_e32 v170, v165
	v_and_b32_e32 v165, 0xffff0000, v172
	v_max_f32_e32 v165, v165, v165
	v_max_f32_e32 v165, 0x358637bd, v165
	v_rcp_f32_e32 v171, v165
	v_lshlrev_b32_e32 v165, 16, v173
	v_max_f32_e32 v165, v165, v165
	v_pk_mul_f32 v[64:65], v[64:65], v[168:169]
	v_lshlrev_b32_e32 v168, 16, v180
	v_and_b32_e32 v169, 0xffff0000, v180
	v_max_f32_e32 v165, 0x358637bd, v165
	v_pk_mul_f32 v[168:169], v[170:171], v[168:169]
	v_rcp_f32_e32 v170, v165
	v_and_b32_e32 v165, 0xffff0000, v173
	v_max_f32_e32 v165, v165, v165
	v_max_f32_e32 v165, 0x358637bd, v165
	v_rcp_f32_e32 v171, v165
	v_lshlrev_b32_e32 v165, 16, v182
	v_max_f32_e32 v165, v165, v165
	v_pk_mul_f32 v[58:59], v[58:59], v[168:169]
	v_lshlrev_b32_e32 v168, 16, v181
	v_and_b32_e32 v169, 0xffff0000, v181
	v_max_f32_e32 v165, 0x358637bd, v165
	v_pk_mul_f32 v[168:169], v[170:171], v[168:169]
	v_rcp_f32_e32 v170, v165
	v_and_b32_e32 v165, 0xffff0000, v182
	v_max_f32_e32 v165, v165, v165
	v_max_f32_e32 v165, 0x358637bd, v165
	v_rcp_f32_e32 v171, v165
	v_lshlrev_b32_e32 v165, 16, v183
	v_max_f32_e32 v165, v165, v165
	v_pk_mul_f32 v[60:61], v[60:61], v[168:169]
	s_waitcnt vmcnt(4)
	v_lshlrev_b32_e32 v168, 16, v186
	v_and_b32_e32 v169, 0xffff0000, v186
	v_max_f32_e32 v165, 0x358637bd, v165
	v_pk_mul_f32 v[168:169], v[170:171], v[168:169]
	v_rcp_f32_e32 v170, v165
	v_and_b32_e32 v165, 0xffff0000, v183
	v_max_f32_e32 v165, v165, v165
	v_max_f32_e32 v165, 0x358637bd, v165
	v_rcp_f32_e32 v171, v165
	v_lshlrev_b32_e32 v165, 16, v184
	v_max_f32_e32 v165, v165, v165
	v_pk_mul_f32 v[30:31], v[30:31], v[168:169]
	v_lshlrev_b32_e32 v168, 16, v187
	v_and_b32_e32 v169, 0xffff0000, v187
	v_max_f32_e32 v165, 0x358637bd, v165
	v_pk_mul_f32 v[168:169], v[170:171], v[168:169]
	v_rcp_f32_e32 v170, v165
	v_and_b32_e32 v165, 0xffff0000, v184
	v_max_f32_e32 v165, v165, v165
	v_max_f32_e32 v165, 0x358637bd, v165
	v_rcp_f32_e32 v171, v165
	v_lshlrev_b32_e32 v165, 16, v185
	v_max_f32_e32 v165, v165, v165
	v_pk_mul_f32 v[32:33], v[32:33], v[168:169]
	v_lshlrev_b32_e32 v168, 16, v188
	v_and_b32_e32 v169, 0xffff0000, v188
	v_max_f32_e32 v165, 0x358637bd, v165
	v_pk_mul_f32 v[168:169], v[170:171], v[168:169]
	v_rcp_f32_e32 v170, v165
	v_and_b32_e32 v165, 0xffff0000, v185
	v_max_f32_e32 v165, v165, v165
	v_max_f32_e32 v165, 0x358637bd, v165
	v_rcp_f32_e32 v171, v165
	v_pk_mul_f32 v[26:27], v[26:27], v[168:169]
	v_lshlrev_b32_e32 v168, 16, v189
	v_and_b32_e32 v169, 0xffff0000, v189
	v_pk_mul_f32 v[168:169], v[170:171], v[168:169]
	s_waitcnt vmcnt(1)
	v_lshlrev_b32_e32 v165, 16, v142
	v_and_b32_e32 v142, 0xffff0000, v142
	v_pk_mul_f32 v[28:29], v[28:29], v[168:169]
	v_lshlrev_b32_e32 v168, 16, v138
	v_and_b32_e32 v169, 0xffff0000, v138
	v_lshlrev_b32_e32 v138, 16, v143
	v_max_f32_e32 v142, v142, v142
	v_max_f32_e32 v138, v138, v138
	v_max_f32_e32 v142, 0x358637bd, v142
	v_max_f32_e32 v138, 0x358637bd, v138
	v_rcp_f32_e32 v171, v142
	v_rcp_f32_e32 v142, v138
	v_and_b32_e32 v138, 0xffff0000, v143
	v_max_f32_e32 v138, v138, v138
	v_max_f32_e32 v138, 0x358637bd, v138
	v_rcp_f32_e32 v143, v138
	v_lshlrev_b32_e32 v138, 16, v139
	v_and_b32_e32 v139, 0xffff0000, v139
	v_max_f32_e32 v165, v165, v165
	v_pk_mul_f32 v[138:139], v[142:143], v[138:139]
	v_lshlrev_b32_e32 v142, 16, v144
	v_and_b32_e32 v143, 0xffff0000, v144
	v_max_f32_e32 v142, v142, v142
	v_max_f32_e32 v143, v143, v143
	v_max_f32_e32 v142, 0x358637bd, v142
	v_max_f32_e32 v143, 0x358637bd, v143
	v_max_f32_e32 v165, 0x358637bd, v165
	v_rcp_f32_e32 v142, v142
	v_rcp_f32_e32 v143, v143
	v_rcp_f32_e32 v170, v165
	v_pk_mul_f32 v[56:57], v[56:57], v[138:139]
	v_lshlrev_b32_e32 v138, 16, v140
	v_and_b32_e32 v139, 0xffff0000, v140
	v_pk_mul_f32 v[138:139], v[142:143], v[138:139]
	v_mad_i64_i32 v[142:143], s[0:1], v166, s67, v[176:177]
	v_pk_mul_f32 v[168:169], v[170:171], v[168:169]
	v_add_co_u32_e32 v170, vcc, s68, v142
	v_pk_mul_f32 v[54:55], v[54:55], v[168:169]
	s_nop 0
	v_addc_co_u32_e32 v171, vcc, 0, v143, vcc
	global_load_dwordx4 v[166:169], v[238:239], off nt
	v_lshlrev_b32_e32 v140, 16, v145
	v_max_f32_e32 v140, v140, v140
	v_add_co_u32_e32 v174, vcc, s69, v142
	v_max_f32_e32 v140, 0x358637bd, v140
	s_nop 0
	v_addc_co_u32_e32 v175, vcc, 0, v143, vcc
	v_rcp_f32_e32 v172, v140
	v_and_b32_e32 v140, 0xffff0000, v145
	global_load_dwordx4 v[142:145], v[230:231], off nt
	v_max_f32_e32 v140, v140, v140
	v_max_f32_e32 v140, 0x358637bd, v140
	v_rcp_f32_e32 v173, v140
	v_pk_mul_f32 v[50:51], v[50:51], v[138:139]
	v_lshlrev_b32_e32 v138, 16, v141
	v_and_b32_e32 v139, 0xffff0000, v141
	v_pk_mul_f32 v[138:139], v[172:173], v[138:139]
	s_waitcnt vmcnt(2)
	v_lshlrev_b32_e32 v140, 16, v134
	v_and_b32_e32 v134, 0xffff0000, v134
	v_pk_mul_f32 v[52:53], v[52:53], v[138:139]
	v_lshlrev_b32_e32 v138, 16, v130
	v_and_b32_e32 v139, 0xffff0000, v130
	v_lshlrev_b32_e32 v130, 16, v135
	v_max_f32_e32 v134, v134, v134
	v_max_f32_e32 v130, v130, v130
	v_max_f32_e32 v140, v140, v140
	v_max_f32_e32 v134, 0x358637bd, v134
	v_max_f32_e32 v130, 0x358637bd, v130
	v_max_f32_e32 v140, 0x358637bd, v140
	v_rcp_f32_e32 v141, v134
	v_rcp_f32_e32 v134, v130
	v_and_b32_e32 v130, 0xffff0000, v135
	v_rcp_f32_e32 v140, v140
	v_max_f32_e32 v130, v130, v130
	v_max_f32_e32 v130, 0x358637bd, v130
	v_rcp_f32_e32 v135, v130
	v_pk_mul_f32 v[138:139], v[140:141], v[138:139]
	v_lshlrev_b32_e32 v130, 16, v131
	v_pk_mul_f32 v[22:23], v[22:23], v[138:139]
	v_and_b32_e32 v131, 0xffff0000, v131
	global_load_dwordx4 v[138:141], v[238:239], off offset:1024 nt
	v_pk_mul_f32 v[130:131], v[134:135], v[130:131]
	v_lshlrev_b32_e32 v134, 16, v136
	v_and_b32_e32 v135, 0xffff0000, v136
	v_max_f32_e32 v134, v134, v134
	v_max_f32_e32 v135, v135, v135
	v_max_f32_e32 v134, 0x358637bd, v134
	v_max_f32_e32 v135, 0x358637bd, v135
	v_rcp_f32_e32 v134, v134
	v_rcp_f32_e32 v135, v135
	v_pk_mul_f32 v[24:25], v[24:25], v[130:131]
	v_lshlrev_b32_e32 v130, 16, v132
	v_and_b32_e32 v131, 0xffff0000, v132
	v_lshlrev_b32_e32 v132, 16, v137
	v_max_f32_e32 v132, v132, v132
	v_max_f32_e32 v132, 0x358637bd, v132
	global_load_dwordx4 v[170:173], v[230:231], off offset:1024 nt
	v_pk_mul_f32 v[130:131], v[134:135], v[130:131]
	v_rcp_f32_e32 v134, v132
	v_and_b32_e32 v132, 0xffff0000, v137
	v_max_f32_e32 v132, v132, v132
	v_max_f32_e32 v132, 0x358637bd, v132
	v_rcp_f32_e32 v135, v132
	v_pk_mul_f32 v[18:19], v[18:19], v[130:131]
	v_lshlrev_b32_e32 v130, 16, v133
	v_and_b32_e32 v131, 0xffff0000, v133
	v_pk_mul_f32 v[130:131], v[134:135], v[130:131]
	v_rcp_f32_e32 v204, v204
	v_pk_mul_f32 v[20:21], v[20:21], v[130:131]
	v_mad_i64_i32 v[130:131], s[0:1], v164, s67, v[176:177]
	v_add_co_u32_e32 v132, vcc, s69, v130
	v_rcp_f32_e32 v205, v205
	s_nop 0
	v_addc_co_u32_e32 v133, vcc, 0, v131, vcc
	v_add_co_u32_e32 v134, vcc, s68, v130
	v_pk_mul_f32 v[194:195], v[204:205], v[198:199]
	s_waitcnt vmcnt(3)
	v_lshlrev_b32_e32 v136, 16, v166
	v_max_f32_e32 v136, v136, v136
	v_max_f32_e32 v136, 0x358637bd, v136
	v_rcp_f32_e32 v164, v136
	v_and_b32_e32 v136, 0xffff0000, v166
	v_max_f32_e32 v136, v136, v136
	v_addc_co_u32_e32 v135, vcc, 0, v131, vcc
	v_max_f32_e32 v136, 0x358637bd, v136
	global_load_dwordx4 v[174:177], v[230:231], off offset:2048 nt
	s_nop 0
	global_load_dwordx4 v[130:133], v[230:231], off offset:3072 nt
	v_rcp_f32_e32 v165, v136
	global_load_dwordx4 v[178:181], v[238:239], off offset:2048 nt
	s_nop 0
	global_load_dwordx4 v[134:137], v[238:239], off offset:3072 nt
	s_waitcnt vmcnt(6)
	v_lshlrev_b32_e32 v182, 16, v142
	v_and_b32_e32 v183, 0xffff0000, v142
	v_lshlrev_b32_e32 v142, 16, v167
	v_max_f32_e32 v142, v142, v142
	v_max_f32_e32 v142, 0x358637bd, v142
	v_rcp_f32_e32 v166, v142
	v_and_b32_e32 v142, 0xffff0000, v167
	v_max_f32_e32 v142, v142, v142
	v_max_f32_e32 v142, 0x358637bd, v142
	v_pk_mul_f32 v[164:165], v[164:165], v[182:183]
	v_rcp_f32_e32 v167, v142
	v_pk_mul_f32 v[46:47], v[46:47], v[164:165]
	v_lshlrev_b32_e32 v164, 16, v168
	v_and_b32_e32 v165, 0xffff0000, v168
	v_max_f32_e32 v164, v164, v164
	v_max_f32_e32 v165, v165, v165
	v_lshlrev_b32_e32 v142, 16, v143
	v_and_b32_e32 v143, 0xffff0000, v143
	v_max_f32_e32 v164, 0x358637bd, v164
	v_max_f32_e32 v165, 0x358637bd, v165
	v_pk_mul_f32 v[142:143], v[166:167], v[142:143]
	v_rcp_f32_e32 v164, v164
	v_rcp_f32_e32 v165, v165
	v_pk_mul_f32 v[48:49], v[48:49], v[142:143]
	v_lshlrev_b32_e32 v142, 16, v144
	v_and_b32_e32 v143, 0xffff0000, v144
	v_lshlrev_b32_e32 v144, 16, v169
	v_max_f32_e32 v144, v144, v144
	v_max_f32_e32 v144, 0x358637bd, v144
	v_pk_mul_f32 v[142:143], v[164:165], v[142:143]
	v_rcp_f32_e32 v164, v144
	v_and_b32_e32 v144, 0xffff0000, v169
	v_max_f32_e32 v144, v144, v144
	v_max_f32_e32 v144, 0x358637bd, v144
	v_rcp_f32_e32 v165, v144
	s_waitcnt vmcnt(5)
	v_lshlrev_b32_e32 v144, 16, v138
	v_and_b32_e32 v138, 0xffff0000, v138
	v_max_f32_e32 v138, v138, v138
	v_max_f32_e32 v144, v144, v144
	v_max_f32_e32 v138, 0x358637bd, v138
	v_pk_mul_f32 v[42:43], v[42:43], v[142:143]
	v_lshlrev_b32_e32 v142, 16, v145
	v_and_b32_e32 v143, 0xffff0000, v145
	v_max_f32_e32 v144, 0x358637bd, v144
	v_rcp_f32_e32 v145, v138
	v_lshlrev_b32_e32 v138, 16, v139
	v_and_b32_e32 v139, 0xffff0000, v139
	v_rcp_f32_e32 v144, v144
	v_max_f32_e32 v138, v138, v138
	v_max_f32_e32 v139, v139, v139
	v_max_f32_e32 v138, 0x358637bd, v138
	v_max_f32_e32 v139, 0x358637bd, v139
	v_pk_mul_f32 v[142:143], v[164:165], v[142:143]
	v_rcp_f32_e32 v138, v138
	v_rcp_f32_e32 v139, v139
	v_pk_mul_f32 v[44:45], v[44:45], v[142:143]
	s_waitcnt vmcnt(4)
	v_lshlrev_b32_e32 v142, 16, v170
	v_and_b32_e32 v143, 0xffff0000, v170
	v_pk_mul_f32 v[142:143], v[144:145], v[142:143]
	v_pk_mul_f32 v[94:95], v[94:95], v[194:195]
	v_pk_mul_f32 v[14:15], v[14:15], v[142:143]
	v_lshlrev_b32_e32 v142, 16, v171
	v_and_b32_e32 v143, 0xffff0000, v171
	v_pk_mul_f32 v[138:139], v[138:139], v[142:143]
	v_lshlrev_b32_e32 v142, 16, v140
	v_and_b32_e32 v140, 0xffff0000, v140
	v_max_f32_e32 v140, v140, v140
	v_max_f32_e32 v142, v142, v142
	v_max_f32_e32 v140, 0x358637bd, v140
	v_max_f32_e32 v142, 0x358637bd, v142
	v_rcp_f32_e32 v143, v140
	v_lshlrev_b32_e32 v140, 16, v141
	v_and_b32_e32 v141, 0xffff0000, v141
	v_rcp_f32_e32 v142, v142
	v_max_f32_e32 v140, v140, v140
	v_max_f32_e32 v141, v141, v141
	v_max_f32_e32 v140, 0x358637bd, v140
	v_max_f32_e32 v141, 0x358637bd, v141
	v_rcp_f32_e32 v140, v140
	v_rcp_f32_e32 v141, v141
	v_pk_mul_f32 v[16:17], v[16:17], v[138:139]
	v_lshlrev_b32_e32 v138, 16, v172
	v_and_b32_e32 v139, 0xffff0000, v172
	v_pk_mul_f32 v[138:139], v[142:143], v[138:139]
	s_nop 0
	v_pk_mul_f32 v[10:11], v[10:11], v[138:139]
	v_lshlrev_b32_e32 v138, 16, v173
	v_and_b32_e32 v139, 0xffff0000, v173
	v_pk_mul_f32 v[138:139], v[140:141], v[138:139]
	s_waitcnt vmcnt(1)
	v_lshlrev_b32_e32 v140, 16, v178
	v_and_b32_e32 v141, 0xffff0000, v178
	v_max_f32_e32 v140, v140, v140
	v_max_f32_e32 v141, v141, v141
	v_max_f32_e32 v140, 0x358637bd, v140
	v_max_f32_e32 v141, 0x358637bd, v141
	v_rcp_f32_e32 v140, v140
	v_rcp_f32_e32 v141, v141
	v_pk_mul_f32 v[12:13], v[12:13], v[138:139]
	v_lshlrev_b32_e32 v138, 16, v174
	v_and_b32_e32 v139, 0xffff0000, v174
	v_pk_mul_f32 v[138:139], v[140:141], v[138:139]
	v_lshlrev_b32_e32 v140, 16, v179
	v_and_b32_e32 v141, 0xffff0000, v179
	v_max_f32_e32 v140, v140, v140
	v_max_f32_e32 v141, v141, v141
	v_max_f32_e32 v140, 0x358637bd, v140
	v_max_f32_e32 v141, 0x358637bd, v141
	v_rcp_f32_e32 v140, v140
	v_rcp_f32_e32 v141, v141
	v_pk_mul_f32 v[38:39], v[38:39], v[138:139]
	v_lshlrev_b32_e32 v138, 16, v175
	v_and_b32_e32 v139, 0xffff0000, v175
	v_pk_mul_f32 v[138:139], v[140:141], v[138:139]
	v_lshlrev_b32_e32 v140, 16, v180
	v_and_b32_e32 v141, 0xffff0000, v180
	v_max_f32_e32 v140, v140, v140
	v_max_f32_e32 v141, v141, v141
	v_max_f32_e32 v140, 0x358637bd, v140
	v_max_f32_e32 v141, 0x358637bd, v141
	v_rcp_f32_e32 v140, v140
	v_rcp_f32_e32 v141, v141
	v_pk_mul_f32 v[40:41], v[40:41], v[138:139]
	v_lshlrev_b32_e32 v138, 16, v176
	v_and_b32_e32 v139, 0xffff0000, v176
	v_pk_mul_f32 v[138:139], v[140:141], v[138:139]
	v_lshlrev_b32_e32 v140, 16, v181
	v_and_b32_e32 v141, 0xffff0000, v181
	v_max_f32_e32 v140, v140, v140
	v_max_f32_e32 v141, v141, v141
	v_max_f32_e32 v140, 0x358637bd, v140
	v_max_f32_e32 v141, 0x358637bd, v141
	v_rcp_f32_e32 v140, v140
	v_rcp_f32_e32 v141, v141
	v_pk_mul_f32 v[34:35], v[34:35], v[138:139]
	v_lshlrev_b32_e32 v138, 16, v177
	v_and_b32_e32 v139, 0xffff0000, v177
	v_pk_mul_f32 v[138:139], v[140:141], v[138:139]
	s_waitcnt vmcnt(0)
	v_lshlrev_b32_e32 v140, 16, v134
	v_and_b32_e32 v134, 0xffff0000, v134
	v_pk_mul_f32 v[36:37], v[36:37], v[138:139]
	v_lshlrev_b32_e32 v138, 16, v130
	v_and_b32_e32 v139, 0xffff0000, v130
	v_lshlrev_b32_e32 v130, 16, v135
	v_max_f32_e32 v134, v134, v134
	v_max_f32_e32 v130, v130, v130
	v_max_f32_e32 v134, 0x358637bd, v134
	v_max_f32_e32 v130, 0x358637bd, v130
	v_rcp_f32_e32 v141, v134
	v_rcp_f32_e32 v134, v130
	v_and_b32_e32 v130, 0xffff0000, v135
	v_max_f32_e32 v130, v130, v130
	v_max_f32_e32 v130, 0x358637bd, v130
	v_rcp_f32_e32 v135, v130
	v_lshlrev_b32_e32 v130, 16, v131
	v_and_b32_e32 v131, 0xffff0000, v131
	v_max_f32_e32 v140, v140, v140
	v_pk_mul_f32 v[130:131], v[134:135], v[130:131]
	v_lshlrev_b32_e32 v134, 16, v136
	v_and_b32_e32 v135, 0xffff0000, v136
	v_max_f32_e32 v134, v134, v134
	v_max_f32_e32 v135, v135, v135
	v_max_f32_e32 v134, 0x358637bd, v134
	v_max_f32_e32 v135, 0x358637bd, v135
	v_rcp_f32_e32 v134, v134
	v_rcp_f32_e32 v135, v135
	v_pk_mul_f32 v[8:9], v[8:9], v[130:131]
	v_lshlrev_b32_e32 v130, 16, v132
	v_and_b32_e32 v131, 0xffff0000, v132
	v_lshlrev_b32_e32 v132, 16, v137
	v_max_f32_e32 v132, v132, v132
	v_max_f32_e32 v132, 0x358637bd, v132
	v_pk_mul_f32 v[130:131], v[134:135], v[130:131]
	v_rcp_f32_e32 v134, v132
	v_and_b32_e32 v132, 0xffff0000, v137
	v_max_f32_e32 v132, v132, v132
	v_max_f32_e32 v140, 0x358637bd, v140
	v_max_f32_e32 v132, 0x358637bd, v132
	v_rcp_f32_e32 v140, v140
	v_rcp_f32_e32 v135, v132
	v_pk_mul_f32 v[2:3], v[2:3], v[130:131]
	v_lshlrev_b32_e32 v130, 16, v133
	v_and_b32_e32 v131, 0xffff0000, v133
	v_pk_mul_f32 v[138:139], v[140:141], v[138:139]
	v_pk_mul_f32 v[130:131], v[134:135], v[130:131]
	v_pk_mul_f32 v[6:7], v[6:7], v[138:139]
	v_pk_mul_f32 v[4:5], v[4:5], v[130:131]

	.amdhsa_kernel _Z6mk_fwd4Args
		.amdhsa_group_segment_fixed_size 0
		.amdhsa_private_segment_fixed_size 0
		.amdhsa_kernarg_size 432
		.amdhsa_user_sgpr_count 2
		.amdhsa_user_sgpr_dispatch_ptr 0
		.amdhsa_user_sgpr_queue_ptr 0
		.amdhsa_user_sgpr_kernarg_segment_ptr 1
		.amdhsa_user_sgpr_dispatch_id 0
		.amdhsa_user_sgpr_kernarg_preload_length 0
		.amdhsa_user_sgpr_kernarg_preload_offset 0
		.amdhsa_user_sgpr_private_segment_size 0
		.amdhsa_uses_dynamic_stack 0
		.amdhsa_enable_private_segment 0
		.amdhsa_system_sgpr_workgroup_id_x 1
		.amdhsa_system_sgpr_workgroup_id_y 0
		.amdhsa_system_sgpr_workgroup_id_z 0
		.amdhsa_system_sgpr_workgroup_info 0
		.amdhsa_system_vgpr_workitem_id 0
		.amdhsa_next_free_vgpr 240
		.amdhsa_next_free_sgpr 102
		.amdhsa_accum_offset 240
		.amdhsa_reserve_vcc 1
		.amdhsa_float_round_mode_32 0
		.amdhsa_float_round_mode_16_64 0
		.amdhsa_float_denorm_mode_32 3
		.amdhsa_float_denorm_mode_16_64 3
		.amdhsa_dx10_clamp 1
		.amdhsa_ieee_mode 1
		.amdhsa_fp16_overflow 0
		.amdhsa_tg_split 0
		.amdhsa_exception_fp_ieee_invalid_op 0
		.amdhsa_exception_fp_denorm_src 0
		.amdhsa_exception_fp_ieee_div_zero 0
		.amdhsa_exception_fp_ieee_overflow 0
		.amdhsa_exception_fp_ieee_underflow 0
		.amdhsa_exception_fp_ieee_inexact 0
		.amdhsa_exception_int_div_zero 0
	.end_amdhsa_kernel

amdhsa.kernels:
  - .agpr_count:     0
    .args:
      - .offset:         0
        .size:           176
        .value_kind:     by_value
      - .offset:         176
        .size:           4
        .value_kind:     hidden_block_count_x
      - .offset:         180
        .size:           4
        .value_kind:     hidden_block_count_y
      - .offset:         184
        .size:           4
        .value_kind:     hidden_block_count_z
      - .offset:         188
        .size:           2
        .value_kind:     hidden_group_size_x
      - .offset:         190
        .size:           2
        .value_kind:     hidden_group_size_y
      - .offset:         192
        .size:           2
        .value_kind:     hidden_group_size_z
      - .offset:         194
        .size:           2
        .value_kind:     hidden_remainder_x
      - .offset:         196
        .size:           2
        .value_kind:     hidden_remainder_y
      - .offset:         198
        .size:           2
        .value_kind:     hidden_remainder_z
      - .offset:         216
        .size:           8
        .value_kind:     hidden_global_offset_x
      - .offset:         224
        .size:           8
        .value_kind:     hidden_global_offset_y
      - .offset:         232
        .size:           8
        .value_kind:     hidden_global_offset_z
      - .offset:         240
        .size:           2
        .value_kind:     hidden_grid_dims
      - .offset:         296
        .size:           4
        .value_kind:     hidden_dynamic_lds_size
    .group_segment_fixed_size: 0
    .kernarg_segment_align: 8
    .kernarg_segment_size: 432
    .language:       OpenCL C
    .language_version:
      - 2
      - 0
    .max_flat_workgroup_size: 512
    .name:           _Z6mk_fwd4Args
    .private_segment_fixed_size: 0
    .sgpr_count:     108
    .sgpr_spill_count: 145
    .symbol:         _Z6mk_fwd4Args.kd
    .uniform_work_group_size: 1
    .uses_dynamic_stack: false
    .vgpr_count:     240
    .vgpr_spill_count: 0
    .wavefront_size: 64
